# m2 static schedule rebalanced: blocks with a latent global-attention job take 2 gla_m2 chunk jobs, the others 6 (was 4 each)
# speedup vs baseline: 1.0047x; 1.0001x over previous
.LBB0_642:
	s_cmp_lt_u32 s54, 0x80
	s_cselect_b32 s100, 2, 6
	v_cmp_eq_u32_e64 s[0:1], 0, v180
	s_and_saveexec_b64 s[2:3], s[0:1]
	s_cbranch_execz .Lpw_done0
	v_readlane_b32 s4, v254, 2
	v_readlane_b32 s5, v254, 3
	v_mov_b32_e32 v0, 0
	s_mov_b32 s12, 0
	s_min_u32 s14, s64, 0x100
	s_nop 4

.LBB0_643:
	v_lshrrev_b32_e32 v1, 4, v171
	v_lshlrev_b32_e32 v7, 1, v120
	v_mul_lo_u32 v1, v1, s85
	v_and_b32_e32 v7, 0x78, v7
	v_add3_u32 v1, 0, v1, v7
	s_waitcnt lgkmcnt(0)
	s_barrier
	s_waitcnt vmcnt(6)
	v_cvt_pk_bf16_f32 v2, v132, v133
	s_waitcnt vmcnt(4)
	v_cvt_pk_bf16_f32 v3, v134, v135
	s_waitcnt vmcnt(2)
	v_cvt_pk_bf16_f32 v4, v128, v129
	s_waitcnt vmcnt(0)
	v_cvt_pk_bf16_f32 v5, v130, v131
	ds_write2_b64 v1, v[2:3], v[4:5] offset1:16
	v_lshrrev_b32_e32 v1, 4, v172
	v_mul_lo_u32 v1, v1, s85
	v_add3_u32 v1, 0, v1, v7
	v_cvt_pk_bf16_f32 v2, v140, v141
	v_cvt_pk_bf16_f32 v3, v142, v143
	v_cvt_pk_bf16_f32 v4, v136, v137
	v_cvt_pk_bf16_f32 v5, v138, v139
	ds_write2_b64 v1, v[2:3], v[4:5] offset1:16
	v_lshrrev_b32_e32 v1, 4, v173
	v_mul_lo_u32 v1, v1, s85
	v_add3_u32 v1, 0, v1, v7
	v_cvt_pk_bf16_f32 v2, v148, v149
	v_cvt_pk_bf16_f32 v3, v150, v151
	v_cvt_pk_bf16_f32 v4, v144, v145
	v_cvt_pk_bf16_f32 v5, v146, v147
	ds_write2_b64 v1, v[2:3], v[4:5] offset1:16
	v_lshrrev_b32_e32 v1, 4, v174
	v_mul_lo_u32 v1, v1, s85
	v_ashrrev_i32_e32 v30, 6, v171
	v_add3_u32 v1, 0, v1, v7
	v_cvt_pk_bf16_f32 v2, v156, v157
	v_cvt_pk_bf16_f32 v3, v158, v159
	v_cvt_pk_bf16_f32 v4, v152, v153
	v_cvt_pk_bf16_f32 v5, v154, v155
	ds_write2_b64 v1, v[2:3], v[4:5] offset1:16
	v_lshlrev_b32_e32 v1, 5, v30
	v_and_b32_e32 v31, 32, v1
	v_bfi_b32 v1, -16, v170, v171
	v_and_b32_e32 v0, 15, v171
	v_mul_lo_u32 v2, v1, s87
	v_and_b32_e32 v32, 48, v171
	v_add3_u32 v33, s86, v2, v32
	v_add3_u32 v35, s89, v2, v32
	v_add_u32_e32 v38, 0, v2
	v_or_b32_e32 v2, v31, v0
	v_mul_u32_u24_e32 v2, 0x48, v2
	v_add_u32_e32 v34, s88, v32
	v_lshlrev_b32_e32 v18, 1, v2
	v_bfe_u32 v6, v171, 4, 2
	v_add_u32_e32 v36, s52, v32
	v_add_u32_e32 v14, v34, v18
	v_lshlrev_b32_e32 v37, 2, v6
	v_lshlrev_b32_e32 v39, 3, v6
	ds_read_b128 v[2:5], v33
	ds_read_b128 v[6:9], v14
	ds_read_b128 v[10:13], v33 offset:64
	ds_read_b128 v[14:17], v14 offset:64
	v_add_u32_e32 v26, v36, v18
	ds_read_b128 v[18:21], v35
	ds_read_b128 v[22:25], v26
	s_waitcnt lgkmcnt(0)
	v_mfma_f32_16x16x32_bf16 v[18:21], v[22:25], v[18:21], 0
	ds_read_b128 v[22:25], v35 offset:64
	ds_read_b128 v[26:29], v26 offset:64
	v_add_u32_e32 v43, 0, v32
	v_add_u32_e32 v44, s53, v32
	v_mfma_f32_16x16x32_bf16 v[2:5], v[6:9], v[2:5], 0
	v_or_b32_e32 v6, v31, v37
	v_cmp_le_i32_e32 vcc, v6, v1
	s_mov_b32 s0, 0x800000
	v_mfma_f32_16x16x32_bf16 v[2:5], v[14:17], v[10:13], v[2:5]
	s_add_i32 s60, s60, 1
	s_cmp_eq_u32 s60, s100
	s_waitcnt lgkmcnt(0)
	v_mfma_f32_16x16x32_bf16 v[18:21], v[26:29], v[22:25], v[18:21]
	s_nop 3
	v_cndmask_b32_e32 v2, 0, v2, vcc
	v_cmp_lt_i32_e32 vcc, v6, v1
	s_nop 1
	v_cndmask_b32_e64 v7, v18, 0, vcc
	v_add_f32_e32 v2, v7, v2
	v_or_b32_e32 v7, 1, v6
	v_cndmask_b32_e32 v3, 0, v3, vcc
	v_cmp_ge_i32_e32 vcc, v7, v1
	s_nop 1
	v_cndmask_b32_e32 v7, 0, v19, vcc
	v_add_f32_e32 v3, v7, v3
	v_or_b32_e32 v7, 2, v6
	v_cmp_le_i32_e32 vcc, v7, v1
	v_or_b32_e32 v6, 3, v6
	v_cvt_pk_bf16_f32 v2, v2, v3
	s_nop 0
	v_cndmask_b32_e32 v4, 0, v4, vcc
	v_cmp_ge_i32_e32 vcc, v7, v1
	s_nop 1
	v_cndmask_b32_e32 v7, 0, v20, vcc
	v_cmp_le_i32_e32 vcc, v6, v1
	v_add_f32_e32 v4, v7, v4
	s_nop 0
	v_cndmask_b32_e32 v5, 0, v5, vcc
	v_cmp_ge_i32_e32 vcc, v6, v1
	s_nop 1
	v_cndmask_b32_e32 v6, 0, v21, vcc
	v_add_f32_e32 v5, v6, v5
	v_cvt_pk_bf16_f32 v3, v4, v5
	v_lshlrev_b32_e32 v4, 1, v31
	v_add3_u32 v39, v38, v39, v4
	v_or_b32_e32 v31, 16, v31
	ds_write_b64 v39, v[2:3] offset:36864
	v_or_b32_e32 v2, v31, v0
	v_mul_u32_u24_e32 v2, 0x48, v2
	v_lshlrev_b32_e32 v18, 1, v2
	v_add_u32_e32 v14, v34, v18
	ds_read_b128 v[2:5], v33
	ds_read_b128 v[6:9], v14
	ds_read_b128 v[10:13], v33 offset:64
	ds_read_b128 v[14:17], v14 offset:64
	v_add_u32_e32 v26, v36, v18
	ds_read_b128 v[18:21], v35
	ds_read_b128 v[22:25], v26
	s_waitcnt lgkmcnt(0)
	v_mfma_f32_16x16x32_bf16 v[18:21], v[22:25], v[18:21], 0
	ds_read_b128 v[22:25], v35 offset:64
	ds_read_b128 v[26:29], v26 offset:64
	v_mfma_f32_16x16x32_bf16 v[2:5], v[6:9], v[2:5], 0
	v_or_b32_e32 v6, v31, v37
	v_cmp_le_i32_e32 vcc, v6, v1
	v_mfma_f32_16x16x32_bf16 v[2:5], v[14:17], v[10:13], v[2:5]
	s_waitcnt lgkmcnt(0)
	v_mfma_f32_16x16x32_bf16 v[18:21], v[26:29], v[22:25], v[18:21]
	s_nop 5
	v_cndmask_b32_e32 v2, 0, v2, vcc
	v_cmp_lt_i32_e32 vcc, v6, v1
	s_nop 1
	v_cndmask_b32_e64 v7, v18, 0, vcc
	v_add_f32_e32 v2, v7, v2
	v_or_b32_e32 v7, 1, v6
	v_cndmask_b32_e32 v3, 0, v3, vcc
	v_cmp_ge_i32_e32 vcc, v7, v1
	s_nop 1
	v_cndmask_b32_e32 v7, 0, v19, vcc
	v_add_f32_e32 v3, v7, v3
	v_or_b32_e32 v7, 2, v6
	v_cmp_le_i32_e32 vcc, v7, v1
	v_or_b32_e32 v6, 3, v6
	v_cvt_pk_bf16_f32 v2, v2, v3
	s_nop 0
	v_cndmask_b32_e32 v4, 0, v4, vcc
	v_cmp_ge_i32_e32 vcc, v7, v1
	s_nop 1
	v_cndmask_b32_e32 v7, 0, v20, vcc
	v_cmp_le_i32_e32 vcc, v6, v1
	v_add_f32_e32 v4, v7, v4
	s_nop 0
	v_cndmask_b32_e32 v5, 0, v5, vcc
	v_cmp_ge_i32_e32 vcc, v6, v1
	s_nop 1
	v_cndmask_b32_e32 v6, 0, v21, vcc
	v_add_f32_e32 v5, v6, v5
	v_cvt_pk_bf16_f32 v3, v4, v5
	ds_write_b64 v39, v[2:3] offset:36896
	v_lshlrev_b32_e32 v2, 2, v30
	v_and_b32_e32 v42, 4, v2
	v_add_u32_e32 v30, v38, v32
	v_lshl_add_u32 v22, v1, 7, v30
	v_lshl_or_b32 v26, v42, 4, v0
	s_waitcnt lgkmcnt(0)
	s_barrier
	v_mad_u32_u24 v23, v26, s85, v43
	ds_read_b128 v[2:5], v22 offset:54272
	ds_read_b128 v[6:9], v23
	ds_read_b128 v[10:13], v22 offset:54336
	ds_read_b128 v[14:17], v23 offset:64
	s_waitcnt lgkmcnt(2)
	v_mfma_f32_16x16x32_bf16 v[6:9], v[6:9], v[2:5], 0
	v_mad_u32_u24 v31, v26, s87, v44
	v_or_b32_e32 v45, 1, v42
	v_lshl_or_b32 v38, v45, 4, v0
	s_waitcnt lgkmcnt(0)
	v_mfma_f32_16x16x32_bf16 v[6:9], v[14:17], v[10:13], v[6:9]
	ds_read_b128 v[14:17], v22 offset:54400
	ds_read_b128 v[18:21], v23 offset:128
	v_mad_u32_u24 v39, v38, s85, v43
	v_mad_u32_u24 v38, v38, s87, v44
	s_waitcnt lgkmcnt(0)
	v_mfma_f32_16x16x32_bf16 v[6:9], v[18:21], v[14:17], v[6:9]
	ds_read_b128 v[18:21], v22 offset:54464
	ds_read_b128 v[22:25], v23 offset:192
	v_or_b32_e32 v46, 2, v42
	v_lshl_or_b32 v47, v46, 4, v0
	s_waitcnt lgkmcnt(0)
	v_mfma_f32_16x16x32_bf16 v[6:9], v[22:25], v[18:21], v[6:9]
	ds_read_b128 v[22:25], v30 offset:36864
	ds_read_b128 v[26:29], v31
	v_mad_u32_u24 v48, v47, s85, v43
	v_mad_u32_u24 v47, v47, s87, v44
	s_waitcnt lgkmcnt(0)
	v_mfma_f32_16x16x32_bf16 v[6:9], v[26:29], v[22:25], v[6:9]
	ds_read_b128 v[26:29], v30 offset:36928
	ds_read_b128 v[30:33], v31 offset:64
	ds_read_b128 v[34:37], v39 offset:64
	s_waitcnt lgkmcnt(1)
	v_mfma_f32_16x16x32_bf16 v[6:9], v[30:33], v[26:29], v[6:9]
	ds_read_b128 v[30:33], v39
	s_waitcnt lgkmcnt(0)
	v_mfma_f32_16x16x32_bf16 v[30:33], v[30:33], v[2:5], 0
	v_mfma_f32_16x16x32_bf16 v[30:33], v[34:37], v[10:13], v[30:33]
	ds_read_b128 v[34:37], v39 offset:128
	s_waitcnt lgkmcnt(0)
	v_mfma_f32_16x16x32_bf16 v[30:33], v[34:37], v[14:17], v[30:33]
	ds_read_b128 v[34:37], v39 offset:192
	s_waitcnt lgkmcnt(0)
	v_mfma_f32_16x16x32_bf16 v[30:33], v[34:37], v[18:21], v[30:33]
	ds_read_b128 v[34:37], v38
	s_waitcnt lgkmcnt(0)
	v_mfma_f32_16x16x32_bf16 v[30:33], v[34:37], v[22:25], v[30:33]
	ds_read_b128 v[34:37], v38 offset:64
	ds_read_b128 v[38:41], v48 offset:64
	s_waitcnt lgkmcnt(1)
	v_mfma_f32_16x16x32_bf16 v[30:33], v[34:37], v[26:29], v[30:33]
	ds_read_b128 v[34:37], v48
	s_waitcnt lgkmcnt(0)
	v_mfma_f32_16x16x32_bf16 v[34:37], v[34:37], v[2:5], 0
	v_mfma_f32_16x16x32_bf16 v[34:37], v[38:41], v[10:13], v[34:37]
	ds_read_b128 v[38:41], v48 offset:128
	s_waitcnt lgkmcnt(0)
	v_mfma_f32_16x16x32_bf16 v[34:37], v[38:41], v[14:17], v[34:37]
	ds_read_b128 v[38:41], v48 offset:192
	s_waitcnt lgkmcnt(0)
	v_mfma_f32_16x16x32_bf16 v[34:37], v[38:41], v[18:21], v[34:37]
	ds_read_b128 v[38:41], v47
	s_waitcnt lgkmcnt(0)
	v_mfma_f32_16x16x32_bf16 v[34:37], v[38:41], v[22:25], v[34:37]
	ds_read_b128 v[38:41], v47 offset:64
	v_or_b32_e32 v47, 3, v42
	v_lshl_or_b32 v0, v47, 4, v0
	v_mad_u32_u24 v48, v0, s85, v43
	s_waitcnt lgkmcnt(0)
	v_mfma_f32_16x16x32_bf16 v[34:37], v[38:41], v[26:29], v[34:37]
	ds_read_b128 v[38:41], v48
	v_mad_u32_u24 v0, v0, s87, v44
	s_waitcnt lgkmcnt(0)
	v_mfma_f32_16x16x32_bf16 v[2:5], v[38:41], v[2:5], 0
	ds_read_b128 v[38:41], v48 offset:64
	s_waitcnt lgkmcnt(0)
	v_mfma_f32_16x16x32_bf16 v[2:5], v[38:41], v[10:13], v[2:5]
	ds_read_b128 v[10:13], v48 offset:128
	s_waitcnt lgkmcnt(0)
	v_mfma_f32_16x16x32_bf16 v[2:5], v[10:13], v[14:17], v[2:5]
	ds_read_b128 v[10:13], v48 offset:192
	s_waitcnt lgkmcnt(0)
	v_mfma_f32_16x16x32_bf16 v[2:5], v[10:13], v[18:21], v[2:5]
	ds_read_b128 v[10:13], v0
	s_waitcnt lgkmcnt(0)
	v_mfma_f32_16x16x32_bf16 v[2:5], v[10:13], v[22:25], v[2:5]
	ds_read_b128 v[10:13], v0 offset:64
	v_lshl_add_u32 v0, v1, 9, v43
	v_lshl_add_u32 v1, v42, 6, v0
	s_waitcnt lgkmcnt(0)
	v_mfma_f32_16x16x32_bf16 v[2:5], v[10:13], v[26:29], v[2:5]
	s_barrier
	ds_write_b128 v1, v[6:9] offset:54272
	v_lshl_add_u32 v1, v45, 6, v0
	ds_write_b128 v1, v[30:33] offset:54272
	v_lshl_add_u32 v1, v46, 6, v0
	v_lshl_add_u32 v0, v47, 6, v0
	s_nop 1
	ds_write_b128 v0, v[2:5] offset:54272
	v_lshlrev_b32_e32 v0, 9, v170
	v_lshlrev_b32_e32 v28, 2, v176
	v_add3_u32 v0, 0, v0, v28
	ds_write_b128 v1, v[34:37] offset:54272
	s_waitcnt lgkmcnt(0)
	s_barrier
	ds_read_b128 v[20:23], v0 offset:54272
	ds_read_b128 v[8:11], v0 offset:54288
	ds_read_b128 v[4:7], v0 offset:54304
	ds_read_b128 v[0:3], v0 offset:54320
	v_lshlrev_b32_e32 v176, 1, v176
	s_waitcnt lgkmcnt(3)
	v_mul_f32_e32 v14, v21, v21
	v_fmac_f32_e32 v14, v20, v20
	v_fmac_f32_e32 v14, v22, v22
	v_fmac_f32_e32 v14, v23, v23
	s_waitcnt lgkmcnt(2)
	v_fmac_f32_e32 v14, v8, v8
	v_fmac_f32_e32 v14, v9, v9
	v_fmac_f32_e32 v14, v10, v10
	v_fmac_f32_e32 v14, v11, v11
	s_waitcnt lgkmcnt(1)
	v_pk_mul_f32 v[12:13], v[4:5], v[4:5]
	s_nop 0
	v_add_f32_e32 v12, v14, v12
	v_add_f32_e32 v14, v12, v13
	v_pk_mul_f32 v[12:13], v[6:7], v[6:7]
	s_nop 0
	v_add_f32_e32 v12, v14, v12
	v_add_f32_e32 v14, v12, v13
	s_waitcnt lgkmcnt(0)
	v_pk_mul_f32 v[12:13], v[0:1], v[0:1]
	s_nop 0
	v_add_f32_e32 v12, v14, v12
	v_add_f32_e32 v14, v12, v13
	v_pk_mul_f32 v[12:13], v[2:3], v[2:3]
	s_nop 0
	v_add_f32_e32 v12, v14, v12
	v_and_b32_e32 v14, 64, v183
	v_add_f32_e32 v12, v12, v13
	v_xor_b32_e32 v13, 1, v183
	v_add_u32_e32 v14, 64, v14
	v_cmp_lt_i32_e32 vcc, v13, v14
	s_nop 1
	v_cndmask_b32_e32 v13, v183, v13, vcc
	v_lshlrev_b32_e32 v13, 2, v13
	ds_bpermute_b32 v13, v13, v12
	s_waitcnt lgkmcnt(0)
	v_add_f32_e32 v12, v12, v13
	v_xor_b32_e32 v13, 2, v183
	v_cmp_lt_i32_e32 vcc, v13, v14
	s_nop 1
	v_cndmask_b32_e32 v13, v183, v13, vcc
	v_lshlrev_b32_e32 v13, 2, v13
	ds_bpermute_b32 v13, v13, v12
	s_waitcnt lgkmcnt(0)
	v_add_f32_e32 v12, v12, v13
	v_xor_b32_e32 v13, 4, v183
	v_cmp_lt_i32_e32 vcc, v13, v14
	s_nop 1
	v_cndmask_b32_e32 v13, v183, v13, vcc
	v_lshlrev_b32_e32 v13, 2, v13
	ds_bpermute_b32 v13, v13, v12
	s_waitcnt lgkmcnt(0)
	v_add_f32_e32 v12, v12, v13
	v_fmamk_f32 v12, v12, 0x3c000000, v184
	v_cmp_gt_f32_e32 vcc, s0, v12
	v_mul_f32_e32 v13, 0x4b800000, v12
	s_mov_b64 s[0:1], 0x2000
	v_cndmask_b32_e32 v12, v12, v13, vcc
	v_rsq_f32_e32 v12, v12
	s_nop 0
	v_mul_f32_e32 v13, 0x45800000, v12
	v_cndmask_b32_e32 v32, v12, v13, vcc
	v_lshl_add_u64 v[12:13], v[118:119], 0, s[8:9]
	v_lshl_add_u64 v[12:13], v[12:13], 0, v[176:177]
	v_lshl_add_u64 v[16:17], v[12:13], 0, s[0:1]
	s_movk_i32 s0, 0x2000
	v_add_co_u32_e32 v12, vcc, s0, v12
	v_mul_f32_e32 v4, v4, v32
	s_nop 0
	v_addc_co_u32_e32 v13, vcc, 0, v13, vcc
	global_load_dwordx4 v[12:15], v[12:13], off
	s_nop 0
	global_load_dwordx4 v[16:19], v[16:17], off offset:16
	v_mul_f32_e32 v20, v20, v32
	v_mul_f32_e32 v8, v8, v32
	v_mul_f32_e32 v0, v0, v32
	v_mul_f32_e32 v21, v21, v32
	v_mul_f32_e32 v9, v9, v32
	v_mul_f32_e32 v22, v22, v32
	v_mul_f32_e32 v10, v10, v32
	v_mul_f32_e32 v23, v23, v32
	v_mul_f32_e32 v11, v11, v32
	s_waitcnt vmcnt(1)
	v_lshlrev_b32_e32 v46, 16, v12
	v_and_b32_e32 v47, 0xffff0000, v12
	v_lshlrev_b32_e32 v48, 16, v13
	v_and_b32_e32 v45, 0xffff0000, v13
	v_lshlrev_b32_e32 v44, 16, v14
	v_and_b32_e32 v43, 0xffff0000, v14
	v_lshlrev_b32_e32 v42, 16, v15
	v_and_b32_e32 v41, 0xffff0000, v15
	s_waitcnt vmcnt(0)
	v_lshlrev_b32_e32 v40, 16, v16
	v_and_b32_e32 v39, 0xffff0000, v16
	v_lshlrev_b32_e32 v38, 16, v17
	v_and_b32_e32 v37, 0xffff0000, v17
	v_lshlrev_b32_e32 v36, 16, v18
	v_and_b32_e32 v35, 0xffff0000, v18
	v_lshlrev_b32_e32 v34, 16, v19
	v_and_b32_e32 v33, 0xffff0000, v19
	global_load_dwordx4 v[12:15], v28, s[30:31] offset:48
	global_load_dwordx4 v[16:19], v28, s[30:31] offset:32
	global_load_dwordx4 v[24:27], v28, s[30:31] offset:16
	s_nop 0
	global_load_dwordx4 v[28:31], v28, s[30:31]
	s_waitcnt vmcnt(3)
	v_mul_f32_e32 v0, v0, v12
	s_waitcnt vmcnt(2)
	v_mul_f32_e32 v4, v4, v16
	v_mul_f32_e32 v16, 0xbfb8aa3b, v40
	v_exp_f32_e32 v16, v16
	s_waitcnt vmcnt(0)
	v_mul_f32_e32 v20, v28, v20
	v_mul_f32_e32 v28, 0xbfb8aa3b, v46
	v_mul_f32_e32 v8, v8, v24
	v_add_f32_e32 v16, 1.0, v16
	v_rcp_f32_e32 v16, v16
	v_mul_f32_e32 v24, 0xbfb8aa3b, v44
	v_exp_f32_e32 v28, v28
	v_exp_f32_e32 v24, v24
	v_mul_f32_e32 v16, v16, v40
	v_mul_f32_e32 v16, v16, v4
	v_mul_f32_e32 v4, v5, v32
	v_mul_f32_e32 v5, 0xbfb8aa3b, v39
	v_exp_f32_e32 v5, v5
	v_mul_f32_e32 v4, v4, v17
	v_add_f32_e32 v28, 1.0, v28
	v_add_f32_e32 v24, 1.0, v24
	v_add_f32_e32 v5, 1.0, v5
	v_rcp_f32_e32 v5, v5
	v_rcp_f32_e32 v28, v28
	v_rcp_f32_e32 v24, v24
	v_mul_f32_e32 v21, v21, v29
	v_mul_f32_e32 v5, v5, v39
	v_mul_f32_e32 v17, v5, v4
	v_mul_f32_e32 v5, 0xbfb8aa3b, v38
	v_exp_f32_e32 v5, v5
	v_mul_f32_e32 v4, v6, v32
	v_mul_f32_e32 v4, v4, v18
	v_mul_f32_e32 v28, v28, v46
	v_add_f32_e32 v5, 1.0, v5
	v_rcp_f32_e32 v5, v5
	v_mul_f32_e32 v24, v24, v44
	v_mul_f32_e32 v20, v28, v20
	v_mul_f32_e32 v28, 0xbfb8aa3b, v47
	v_mul_f32_e32 v5, v5, v38
	v_mul_f32_e32 v6, v5, v4
	v_mul_f32_e32 v5, 0xbfb8aa3b, v37
	v_exp_f32_e32 v5, v5
	v_mul_f32_e32 v4, v7, v32
	v_mul_f32_e32 v4, v4, v19
	v_mul_f32_e32 v8, v24, v8
	v_add_f32_e32 v5, 1.0, v5
	v_rcp_f32_e32 v5, v5
	v_mul_f32_e32 v24, 0xbfb8aa3b, v43
	v_exp_f32_e32 v28, v28
	v_exp_f32_e32 v24, v24
	v_mul_f32_e32 v5, v5, v37
	v_mul_f32_e32 v7, v5, v4
	v_mul_f32_e32 v4, 0xbfb8aa3b, v36
	v_exp_f32_e32 v4, v4
	v_add_f32_e32 v28, 1.0, v28
	v_add_f32_e32 v24, 1.0, v24
	v_rcp_f32_e32 v28, v28
	v_add_f32_e32 v4, 1.0, v4
	v_rcp_f32_e32 v4, v4
	v_rcp_f32_e32 v24, v24
	v_mul_f32_e32 v28, v28, v47
	v_mul_f32_e32 v9, v9, v25
	v_mul_f32_e32 v4, v4, v36
	v_mul_f32_e32 v12, v4, v0
	v_mul_f32_e32 v0, v1, v32
	v_mul_f32_e32 v1, 0xbfb8aa3b, v35
	v_exp_f32_e32 v1, v1
	v_mul_f32_e32 v0, v0, v13
	v_mul_f32_e32 v24, v24, v43
	v_mul_f32_e32 v21, v28, v21
	v_add_f32_e32 v1, 1.0, v1
	v_rcp_f32_e32 v1, v1
	v_mul_f32_e32 v28, 0xbfb8aa3b, v48
	v_mul_f32_e32 v9, v24, v9
	v_mul_f32_e32 v24, 0xbfb8aa3b, v42
	v_mul_f32_e32 v1, v1, v35
	v_mul_f32_e32 v13, v1, v0
	v_mul_f32_e32 v1, 0xbfb8aa3b, v34
	v_exp_f32_e32 v1, v1
	v_exp_f32_e32 v28, v28
	v_exp_f32_e32 v24, v24
	v_mul_f32_e32 v0, v2, v32
	v_add_f32_e32 v1, 1.0, v1
	v_rcp_f32_e32 v1, v1
	v_add_f32_e32 v28, 1.0, v28
	v_add_f32_e32 v24, 1.0, v24
	v_rcp_f32_e32 v28, v28
	v_rcp_f32_e32 v24, v24
	v_mul_f32_e32 v0, v0, v14
	v_mul_f32_e32 v1, v1, v34
	v_mul_f32_e32 v14, v1, v0
	v_mul_f32_e32 v1, 0xbfb8aa3b, v33
	v_mul_f32_e32 v22, v22, v30
	v_mul_f32_e32 v28, v28, v48
	v_mul_f32_e32 v10, v10, v26
	v_mul_f32_e32 v24, v24, v42
	v_exp_f32_e32 v1, v1
	v_mul_f32_e32 v22, v28, v22
	v_mul_f32_e32 v28, 0xbfb8aa3b, v45
	v_mul_f32_e32 v10, v24, v10
	v_mul_f32_e32 v24, 0xbfb8aa3b, v41
	v_exp_f32_e32 v28, v28
	v_exp_f32_e32 v24, v24
	v_add_f32_e32 v1, 1.0, v1
	v_rcp_f32_e32 v1, v1
	v_add_f32_e32 v28, 1.0, v28
	v_add_f32_e32 v24, 1.0, v24
	v_rcp_f32_e32 v28, v28
	v_rcp_f32_e32 v24, v24
	v_mul_f32_e32 v0, v3, v32
	v_mul_f32_e32 v0, v0, v15
	v_mul_f32_e32 v1, v1, v33
	v_mul_f32_e32 v15, v1, v0
	v_lshlrev_b64 v[0:1], 13, v[116:117]
	v_mul_f32_e32 v23, v23, v31
	v_mul_f32_e32 v28, v28, v45
	v_mul_f32_e32 v11, v11, v27
	v_mul_f32_e32 v24, v24, v41
	v_lshl_add_u64 v[0:1], s[4:5], 0, v[0:1]
	v_mul_f32_e32 v23, v28, v23
	v_mul_f32_e32 v11, v24, v11
	v_lshl_add_u64 v[4:5], v[0:1], 0, v[176:177]
	v_cvt_pk_bf16_f32 v0, v20, v21
	v_cvt_pk_bf16_f32 v1, v22, v23
	v_cvt_pk_bf16_f32 v2, v8, v9
	v_cvt_pk_bf16_f32 v3, v10, v11
	global_store_dwordx4 v[4:5], v[0:3], off offset:2048
	s_nop 1
	v_cvt_pk_bf16_f32 v0, v16, v17
	v_cvt_pk_bf16_f32 v1, v6, v7
	v_cvt_pk_bf16_f32 v2, v12, v13
	v_cvt_pk_bf16_f32 v3, v14, v15
	global_store_dwordx4 v[4:5], v[0:3], off offset:2064
	s_barrier
	s_cbranch_scc1 .LBB0_593
.LBB0_644:
	s_lshr_b32 s0, s54, 3
	s_cmp_lt_u32 s54, 0x80
	s_cbranch_scc1 .Lgreba
	s_add_i32 s0, s0, 16
.Lgreba:
	s_lshl_b32 s12, s60, 4
	s_add_i32 s0, s0, s12
	s_lshl_b32 s0, s0, 3
	s_and_b32 s12, s54, 7
	s_or_b32 s12, s0, s12
	s_mul_i32 s0, s12, 0x8200
	v_mov_b32_e32 v171, v180
	s_mul_hi_i32 s1, s12, 0x8200
	s_add_u32 s0, s46, s0
	s_movk_i32 s2, 0x820
	s_addc_u32 s1, s47, s1
	v_lshlrev_b32_e32 v120, 2, v171
	v_lshlrev_b32_e32 v186, 4, v171
	v_ashrrev_i32_e32 v121, 31, v120
	global_load_dwordx4 v[188:191], v186, s[0:1]
	v_add_u32_e32 v172, 0x200, v171
	v_add_u32_e32 v187, 0x2000, v186
	v_lshlrev_b32_e32 v126, 2, v172
	global_load_dwordx4 v[192:195], v187, s[0:1]
	v_add_u32_e32 v173, 0x400, v171
	v_add_u32_e32 v187, 0x4000, v186
	v_lshlrev_b32_e32 v124, 2, v173
	global_load_dwordx4 v[196:199], v187, s[0:1]
	v_add_u32_e32 v174, 0x600, v171
	v_add_u32_e32 v187, 0x6000, v186
	v_lshlrev_b32_e32 v122, 2, v174
	global_load_dwordx4 v[200:203], v187, s[0:1]
	v_cmp_gt_i32_e32 vcc, 32, v171
	v_add_u32_e32 v187, 0x8000, v186
	s_nop 1
	v_cndmask_b32_e32 v187, 0, v187, vcc
	global_load_dwordx4 v[204:207], v187, s[0:1]
	s_ashr_i32 s61, s12, 3
	s_lshl_b32 s0, s61, 6
	s_cmp_lt_i32 s61, 64
	s_cselect_b64 s[20:21], -1, 0
	s_add_i32 s1, s0, 0xfffff000
	s_lshr_b32 s1, s1, 11
	s_ashr_i32 s2, s12, 5
	s_cmp_gt_i32 s61, 63
	v_readlane_b32 s68, v254, 12
	s_cselect_b64 s[24:25], -1, 0
	v_ashrrev_i32_e32 v170, 3, v171
	v_readlane_b32 s74, v254, 18
	v_readlane_b32 s75, v254, 19
	s_and_b64 vcc, s[24:25], exec
	v_add_u32_e32 v116, s0, v170
	v_mov_b64_e32 v[0:1], s[74:75]
	s_cselect_b32 s13, s1, s2
	v_and_b32_e32 v11, 7, v171
	v_mad_i64_i32 v[118:119], s[0:1], v116, s84, v[0:1]
	s_mov_b32 s7, s9
	v_lshl_add_u64 v[0:1], v[118:119], 0, s[6:7]
	v_lshlrev_b32_e32 v176, 4, v11
	v_lshl_add_u64 v[0:1], v[0:1], 0, v[176:177]
	v_add_co_u32_e64 v4, s[0:1], s92, v0
	s_nop 1
	v_addc_co_u32_e64 v5, s[0:1], 0, v1, s[0:1]
	global_load_dwordx4 v[208:211], v[4:5], off
	global_load_dwordx4 v[212:215], v[4:5], off offset:1024
	s_waitcnt vmcnt(2)
	ds_write_b128 v186, v[188:191]
	ds_write_b128 v186, v[192:195] offset:8192
	ds_write_b128 v186, v[196:199] offset:16384
	ds_write_b128 v186, v[200:203] offset:24576
	v_cmp_gt_i32_e64 s[98:99], 32, v171
	s_and_saveexec_b64 s[62:63], s[98:99]
	ds_write_b128 v186, v[204:207] offset:32768
	s_mov_b64 exec, s[62:63]
	s_waitcnt lgkmcnt(0)
	s_barrier
	v_lshlrev_b32_e32 v8, 5, v11
	v_add_u32_e32 v10, 0, v8
	s_movk_i32 s0, 0x104
	v_mad_u64_u32 v[12:13], s[0:1], v170, s0, v[10:11]
	ds_read2_b32 v[14:15], v12 offset1:1
	v_add_u32_e32 v13, 0x607c, v10
	s_mov_b64 s[0:1], 0x1800
	v_mul_u32_u24_e32 v11, 0x900, v11
	s_lshl_b32 s14, s13, 2
	s_mov_b32 s15, s9
	s_mov_b32 s3, s9
	v_readlane_b32 s69, v254, 13
	v_readlane_b32 s70, v254, 14
	v_readlane_b32 s71, v254, 15
	v_readlane_b32 s72, v254, 16
	v_readlane_b32 s73, v254, 17
	v_readlane_b32 s76, v254, 20
	v_readlane_b32 s77, v254, 21
	v_readlane_b32 s78, v254, 22
	v_readlane_b32 s79, v254, 23
	v_readlane_b32 s80, v254, 24
	v_readlane_b32 s81, v254, 25
	v_readlane_b32 s82, v254, 26
	v_readlane_b32 s83, v254, 27
	s_waitcnt vmcnt(1)
	v_lshlrev_b32_e32 v6, 16, v208
	v_and_b32_e32 v20, 0xffff0000, v208
	v_lshlrev_b32_e32 v32, 16, v209
	v_and_b32_e32 v33, 0xffff0000, v209
	v_lshlrev_b32_e32 v40, 16, v210
	v_and_b32_e32 v41, 0xffff0000, v210
	v_lshlrev_b32_e32 v49, 16, v211
	v_and_b32_e32 v16, 0xffff0000, v211
	v_mul_f32_e32 v17, 0x3e000000, v6
	v_mul_f32_e32 v49, 0x3e000000, v49
	s_waitcnt vmcnt(0)
	v_lshlrev_b32_e32 v22, 16, v212
	v_and_b32_e32 v34, 0xffff0000, v212
	v_add_u32_e32 v0, 0x4100, v12
	v_lshlrev_b32_e32 v35, 16, v213
	v_and_b32_e32 v42, 0xffff0000, v213
	v_lshlrev_b32_e32 v37, 16, v214
	v_and_b32_e32 v50, 0xffff0000, v214
	v_lshlrev_b32_e32 v24, 16, v215
	v_and_b32_e32 v9, 0xffff0000, v215
	ds_read2_b32 v[28:29], v0 offset1:1
	ds_read_b128 v[4:7], v10 offset:8320
	ds_read_b128 v[0:3], v10 offset:8336
	ds_read2_b32 v[30:31], v13 offset1:1
	s_waitcnt lgkmcnt(4)
	v_mul_f32_e32 v13, 0x3fb8aa3b, v14
	v_exp_f32_e32 v13, v13
	s_nop 0
	v_mul_f32_e32 v23, v17, v13
	s_waitcnt lgkmcnt(3)
	v_mul_f32_e32 v13, 0x3fb8aa3b, v28
	v_exp_f32_e32 v13, v13
	s_nop 0
	v_mul_f32_e32 v21, v17, v13
	s_waitcnt lgkmcnt(2)
	v_sub_f32_e32 v13, v14, v4
	v_sub_f32_e32 v4, v4, v14
	v_mul_f32_e32 v4, 0x3fb8aa3b, v4
	v_exp_f32_e32 v4, v4
	v_mul_f32_e32 v13, 0x3fb8aa3b, v13
	v_exp_f32_e32 v13, v13
	v_mul_f32_e32 v14, 0x3fb8aa3b, v15
	v_mul_f32_e32 v18, v4, v22
	s_waitcnt lgkmcnt(0)
	v_sub_f32_e32 v4, v28, v30
	v_mul_f32_e32 v4, 0x3fb8aa3b, v4
	v_exp_f32_e32 v4, v4
	v_mul_f32_e32 v19, v17, v13
	v_exp_f32_e32 v14, v14
	v_mul_f32_e32 v17, v17, v4
	v_sub_f32_e32 v4, v30, v28
	v_mul_f32_e32 v4, 0x3fb8aa3b, v4
	v_exp_f32_e32 v4, v4
	s_nop 0
	v_mul_f32_e32 v13, v4, v22
	v_mul_f32_e32 v4, 0x3e000000, v20
	v_mul_f32_e32 v28, v4, v14
	v_mul_f32_e32 v14, 0x3fb8aa3b, v29
	v_exp_f32_e32 v14, v14
	s_nop 0
	v_mul_f32_e32 v27, v4, v14
	v_sub_f32_e32 v14, v15, v5
	v_sub_f32_e32 v5, v5, v15
	v_mul_f32_e32 v5, 0x3fb8aa3b, v5
	v_exp_f32_e32 v5, v5
	v_mul_f32_e32 v14, 0x3fb8aa3b, v14
	v_exp_f32_e32 v14, v14
	v_mul_f32_e32 v25, v5, v34
	v_sub_f32_e32 v5, v29, v31
	v_mul_f32_e32 v5, 0x3fb8aa3b, v5
	v_exp_f32_e32 v5, v5
	v_mul_f32_e32 v26, v4, v14
	ds_read2_b32 v[14:15], v12 offset0:2 offset1:3
	v_mul_f32_e32 v22, v4, v5
	v_sub_f32_e32 v4, v31, v29
	v_mul_f32_e32 v4, 0x3fb8aa3b, v4
	v_exp_f32_e32 v4, v4
	v_add_u32_e32 v29, 0x6084, v10
	ds_read2_b32 v[38:39], v29 offset1:1
	v_mul_f32_e32 v20, v4, v34
	v_add_u32_e32 v4, 0x4108, v12
	ds_read2_b32 v[4:5], v4 offset1:1
	s_waitcnt lgkmcnt(2)
	v_mul_f32_e32 v29, 0x3fb8aa3b, v14
	v_exp_f32_e32 v29, v29
	v_mul_f32_e32 v34, 0x3e000000, v32
	v_mul_f32_e32 v32, v34, v29
	s_waitcnt lgkmcnt(0)
	v_mul_f32_e32 v29, 0x3fb8aa3b, v4
	v_exp_f32_e32 v29, v29
	s_nop 0
	v_mul_f32_e32 v31, v34, v29
	v_sub_f32_e32 v29, v14, v6
	v_sub_f32_e32 v6, v6, v14
	v_mul_f32_e32 v29, 0x3fb8aa3b, v29
	v_mul_f32_e32 v6, 0x3fb8aa3b, v6
	v_exp_f32_e32 v29, v29
	v_exp_f32_e32 v6, v6
	v_mul_f32_e32 v30, v34, v29
	v_mul_f32_e32 v29, v6, v35
	v_sub_f32_e32 v6, v4, v38
	v_sub_f32_e32 v4, v38, v4
	v_mul_f32_e32 v6, 0x3fb8aa3b, v6
	v_mul_f32_e32 v4, 0x3fb8aa3b, v4
	v_exp_f32_e32 v6, v6
	v_exp_f32_e32 v4, v4
	v_mul_f32_e32 v38, 0x3e000000, v40
	v_mul_f32_e32 v14, v34, v6
	v_mul_f32_e32 v6, v4, v35
	v_mul_f32_e32 v4, 0x3e000000, v33
	v_mul_f32_e32 v33, 0x3fb8aa3b, v15
	v_exp_f32_e32 v33, v33
	s_nop 0
	v_mul_f32_e32 v36, v4, v33
	v_mul_f32_e32 v33, 0x3fb8aa3b, v5
	v_exp_f32_e32 v33, v33
	s_nop 0
	v_mul_f32_e32 v35, v4, v33
	v_sub_f32_e32 v33, v15, v7
	v_sub_f32_e32 v7, v7, v15
	v_mul_f32_e32 v33, 0x3fb8aa3b, v33
	v_mul_f32_e32 v7, 0x3fb8aa3b, v7
	v_exp_f32_e32 v33, v33
	v_exp_f32_e32 v7, v7
	v_mul_f32_e32 v34, v4, v33
	v_mul_f32_e32 v33, v7, v42
	v_sub_f32_e32 v7, v5, v39
	v_mul_f32_e32 v7, 0x3fb8aa3b, v7
	v_exp_f32_e32 v7, v7
	s_nop 0
	v_mul_f32_e32 v15, v4, v7
	v_sub_f32_e32 v4, v39, v5
	v_mul_f32_e32 v4, 0x3fb8aa3b, v4
	v_exp_f32_e32 v4, v4
	v_add_u32_e32 v39, 0x4110, v12
	ds_read2_b32 v[52:53], v39 offset1:1
	v_add_u32_e32 v39, 0x608c, v10
	v_mul_f32_e32 v7, v4, v42
	ds_read2_b32 v[4:5], v12 offset0:4 offset1:5
	ds_read2_b32 v[54:55], v39 offset1:1
	v_add_u32_e32 v10, 0x6094, v10
	s_waitcnt lgkmcnt(1)
	v_mul_f32_e32 v39, 0x3fb8aa3b, v4
	v_exp_f32_e32 v39, v39
	s_nop 0
	v_mul_f32_e32 v44, v38, v39
	v_mul_f32_e32 v39, 0x3fb8aa3b, v52
	v_exp_f32_e32 v39, v39
	s_nop 0
	v_mul_f32_e32 v42, v38, v39
	v_sub_f32_e32 v39, v4, v0
	v_sub_f32_e32 v0, v0, v4
	v_mul_f32_e32 v39, 0x3fb8aa3b, v39
	v_mul_f32_e32 v0, 0x3fb8aa3b, v0
	v_exp_f32_e32 v39, v39
	v_exp_f32_e32 v0, v0
	v_mul_f32_e32 v4, 0x3fb8aa3b, v5
	v_exp_f32_e32 v4, v4
	v_mul_f32_e32 v40, v38, v39
	v_mul_f32_e32 v39, v0, v37
	s_waitcnt lgkmcnt(0)
	v_sub_f32_e32 v0, v52, v54
	v_mul_f32_e32 v0, 0x3fb8aa3b, v0
	v_exp_f32_e32 v0, v0
	s_nop 0
	v_mul_f32_e32 v38, v38, v0
	v_sub_f32_e32 v0, v54, v52
	v_mul_f32_e32 v0, 0x3fb8aa3b, v0
	v_exp_f32_e32 v0, v0
	s_nop 0
	v_mul_f32_e32 v37, v0, v37
	v_mul_f32_e32 v0, 0x3e000000, v41
	v_mul_f32_e32 v48, v0, v4
	v_mul_f32_e32 v4, 0x3fb8aa3b, v53
	v_exp_f32_e32 v4, v4
	s_nop 0
	v_mul_f32_e32 v47, v0, v4
	v_sub_f32_e32 v4, v5, v1
	v_sub_f32_e32 v1, v1, v5
	v_mul_f32_e32 v1, 0x3fb8aa3b, v1
	v_exp_f32_e32 v1, v1
	v_mul_f32_e32 v4, 0x3fb8aa3b, v4
	v_exp_f32_e32 v4, v4
	v_mul_f32_e32 v45, v1, v50
	v_sub_f32_e32 v1, v53, v55
	v_mul_f32_e32 v1, 0x3fb8aa3b, v1
	v_exp_f32_e32 v1, v1
	v_mul_f32_e32 v46, v0, v4
	v_add_u32_e32 v4, 0x4118, v12
	ds_read2_b32 v[4:5], v4 offset1:1
	v_mul_f32_e32 v43, v0, v1
	v_sub_f32_e32 v0, v55, v53
	v_mul_f32_e32 v0, 0x3fb8aa3b, v0
	v_exp_f32_e32 v0, v0
	s_nop 0
	v_mul_f32_e32 v41, v0, v50
	ds_read2_b32 v[0:1], v12 offset0:6 offset1:7
	ds_read2_b32 v[50:51], v10 offset1:1
	s_waitcnt lgkmcnt(2)
	v_mul_f32_e32 v12, 0x3fb8aa3b, v4
	v_exp_f32_e32 v12, v12
	s_waitcnt lgkmcnt(1)
	v_mul_f32_e32 v10, 0x3fb8aa3b, v0
	v_sub_f32_e32 v52, v0, v2
	v_sub_f32_e32 v0, v2, v0
	v_mul_f32_e32 v0, 0x3fb8aa3b, v0
	v_exp_f32_e32 v0, v0
	v_mul_f32_e32 v52, 0x3fb8aa3b, v52
	v_exp_f32_e32 v10, v10
	v_exp_f32_e32 v52, v52
	v_mul_f32_e32 v53, v0, v24
	s_waitcnt lgkmcnt(0)
	v_sub_f32_e32 v0, v4, v50
	v_mul_f32_e32 v0, 0x3fb8aa3b, v0
	v_exp_f32_e32 v0, v0
	v_mul_f32_e32 v10, v49, v10
	v_mul_f32_e32 v12, v49, v12
	v_mul_f32_e32 v52, v49, v52
	v_mul_f32_e32 v49, v49, v0
	v_sub_f32_e32 v0, v50, v4
	v_mul_f32_e32 v0, 0x3fb8aa3b, v0
	v_exp_f32_e32 v0, v0
	v_mul_f32_e32 v2, 0x3fb8aa3b, v1
	v_exp_f32_e32 v2, v2
	v_mul_f32_e32 v4, v0, v24
	v_mul_f32_e32 v0, 0x3e000000, v16
	v_mul_f32_e32 v16, v0, v2
	v_mul_f32_e32 v2, 0x3fb8aa3b, v5
	v_exp_f32_e32 v2, v2
	s_nop 0
	v_mul_f32_e32 v24, v0, v2
	v_sub_f32_e32 v2, v1, v3
	v_sub_f32_e32 v1, v3, v1
	v_mul_f32_e32 v1, 0x3fb8aa3b, v1
	v_exp_f32_e32 v1, v1
	v_mul_f32_e32 v2, 0x3fb8aa3b, v2
	v_exp_f32_e32 v2, v2
	v_mul_f32_e32 v54, v1, v9
	v_sub_f32_e32 v1, v5, v51
	v_mul_f32_e32 v1, 0x3fb8aa3b, v1
	v_exp_f32_e32 v1, v1
	v_mul_f32_e32 v50, v0, v2
	v_mul_f32_e32 v55, v0, v1
	v_sub_f32_e32 v0, v51, v5
	v_mul_f32_e32 v0, 0x3fb8aa3b, v0
	v_exp_f32_e32 v0, v0
	s_nop 0
	v_mul_f32_e32 v5, v0, v9
	v_mul_lo_u32 v9, v170, s85
	v_cvt_pk_bf16_f32 v0, v23, v28
	v_cvt_pk_bf16_f32 v1, v32, v36
	v_cvt_pk_bf16_f32 v2, v44, v48
	v_cvt_pk_bf16_f32 v3, v10, v16
	v_add3_u32 v9, 0, v9, v176
	ds_write_b128 v9, v[0:3] offset:54272
	v_cvt_pk_bf16_f32 v0, v21, v27
	v_cvt_pk_bf16_f32 v1, v31, v35
	v_cvt_pk_bf16_f32 v2, v42, v47
	v_cvt_pk_bf16_f32 v3, v12, v24
	ds_write_b128 v9, v[0:3] offset:54400
	v_mul_lo_u32 v9, v170, s87
	v_cvt_pk_bf16_f32 v0, v19, v26
	v_cvt_pk_bf16_f32 v1, v30, v34
	v_cvt_pk_bf16_f32 v2, v40, v46
	v_cvt_pk_bf16_f32 v3, v52, v50
	v_add3_u32 v10, s86, v9, v176
	ds_write_b128 v10, v[0:3]
	v_cvt_pk_bf16_f32 v0, v18, v25
	v_cvt_pk_bf16_f32 v1, v29, v33
	v_cvt_pk_bf16_f32 v2, v39, v45
	v_cvt_pk_bf16_f32 v3, v53, v54
	v_add3_u32 v10, s88, v9, v176
	ds_write_b128 v10, v[0:3]
	v_cvt_pk_bf16_f32 v0, v17, v22
	v_cvt_pk_bf16_f32 v1, v14, v15
	v_cvt_pk_bf16_f32 v2, v38, v43
	v_cvt_pk_bf16_f32 v3, v49, v55
	v_add3_u32 v10, s89, v9, v176
	ds_write_b128 v10, v[0:3]
	v_cvt_pk_bf16_f32 v0, v13, v20
	v_cvt_pk_bf16_f32 v1, v6, v7
	v_cvt_pk_bf16_f32 v2, v37, v41
	v_cvt_pk_bf16_f32 v3, v4, v5
	v_add3_u32 v4, s52, v9, v176
	ds_write_b128 v4, v[0:3]
	v_lshl_add_u64 v[0:1], v[118:119], 0, s[8:9]
	v_mov_b32_e32 v9, v177
	v_lshl_add_u64 v[0:1], v[0:1], 0, v[8:9]
	v_lshl_add_u64 v[4:5], v[0:1], 0, s[0:1]
	v_add_co_u32_e64 v0, s[0:1], s92, v0
	v_lshlrev_b32_e32 v17, 1, v170
	s_nop 0
	v_addc_co_u32_e64 v1, s[0:1], 0, v1, s[0:1]
	global_load_dwordx4 v[0:3], v[0:1], off offset:2048
	s_nop 0
	global_load_dwordx4 v[4:7], v[4:5], off offset:16
	v_add3_u32 v11, s53, v17, v11
	s_lshl_b64 s[0:1], s[14:15], 18
	s_add_u32 s0, s56, s0
	s_addc_u32 s1, s57, s1
	s_or_b32 s2, s14, 1
	s_waitcnt vmcnt(1)
	v_lshlrev_b32_e32 v8, 16, v0
	v_and_b32_e32 v0, 0xffff0000, v0
	v_cvt_pk_bf16_f32 v8, v8, v177
	ds_write_b16 v11, v8
	v_cvt_pk_bf16_f32 v0, v0, v177
	v_lshlrev_b32_e32 v9, 16, v1
	ds_write_b16 v11, v0 offset:144
	v_cvt_pk_bf16_f32 v0, v9, v177
	v_and_b32_e32 v1, 0xffff0000, v1
	ds_write_b16 v11, v0 offset:288
	v_cvt_pk_bf16_f32 v0, v1, v177
	v_lshlrev_b32_e32 v10, 16, v2
	ds_write_b16 v11, v0 offset:432
	v_cvt_pk_bf16_f32 v0, v10, v177
	v_and_b32_e32 v2, 0xffff0000, v2
	ds_write_b16 v11, v0 offset:576
	v_cvt_pk_bf16_f32 v0, v2, v177
	v_lshlrev_b32_e32 v12, 16, v3
	ds_write_b16 v11, v0 offset:720
	v_cvt_pk_bf16_f32 v0, v12, v177
	v_and_b32_e32 v3, 0xffff0000, v3
	ds_write_b16 v11, v0 offset:864
	v_cvt_pk_bf16_f32 v0, v3, v177
	s_waitcnt vmcnt(0)
	v_lshlrev_b32_e32 v13, 16, v4
	ds_write_b16 v11, v0 offset:1008
	v_cvt_pk_bf16_f32 v0, v13, v177
	v_and_b32_e32 v4, 0xffff0000, v4
	ds_write_b16 v11, v0 offset:1152
	v_cvt_pk_bf16_f32 v0, v4, v177
	v_lshlrev_b32_e32 v14, 16, v5
	ds_write_b16 v11, v0 offset:1296
	v_cvt_pk_bf16_f32 v0, v14, v177
	v_and_b32_e32 v5, 0xffff0000, v5
	ds_write_b16 v11, v0 offset:1440
	v_cvt_pk_bf16_f32 v0, v5, v177
	v_lshlrev_b32_e32 v15, 16, v6
	ds_write_b16 v11, v0 offset:1584
	v_cvt_pk_bf16_f32 v0, v15, v177
	v_and_b32_e32 v6, 0xffff0000, v6
	ds_write_b16 v11, v0 offset:1728
	v_cvt_pk_bf16_f32 v0, v6, v177
	v_lshlrev_b32_e32 v16, 16, v7
	ds_write_b16 v11, v0 offset:1872
	v_cvt_pk_bf16_f32 v0, v16, v177
	v_and_b32_e32 v7, 0xffff0000, v7
	ds_write_b16 v11, v0 offset:2016
	v_cvt_pk_bf16_f32 v0, v7, v177
	ds_write_b16 v11, v0 offset:2160
	v_lshlrev_b32_e32 v0, 11, v171
	v_and_b32_e32 v2, 0x7800, v0
	v_mov_b32_e32 v3, v177
	v_lshl_add_u64 v[0:1], s[0:1], 0, v[2:3]
	s_lshl_b64 s[0:1], s[2:3], 18
	s_add_u32 s0, s56, s0
	s_addc_u32 s1, s57, s1
	v_lshl_add_u64 v[2:3], s[0:1], 0, v[2:3]
	s_cbranch_vccz .LBB0_659
	v_readlane_b32 s68, v254, 16
	v_readlane_b32 s69, v254, 17
	s_sub_i32 s70, s61, 64
	s_lshl_b32 s70, s70, 3
	s_or_b32 s70, s70, s55
	s_mov_b32 s71, 0
	s_lshl_b64 s[70:71], s[70:71], 16
	s_add_u32 s68, s68, s70
	s_addc_u32 s69, s69, s71
	s_add_u32 s70, s68, 0x8000
	s_addc_u32 s71, s69, 0
	v_lshlrev_b32_e32 v186, 4, v171
	global_load_dwordx4 v[132:135], v186, s[68:69]
	global_load_dwordx4 v[128:131], v186, s[70:71]
	v_add_u32_e32 v187, 0x2000, v186
	global_load_dwordx4 v[140:143], v187, s[68:69]
	global_load_dwordx4 v[136:139], v187, s[70:71]
	v_add_u32_e32 v187, 0x4000, v186
	global_load_dwordx4 v[148:151], v187, s[68:69]
	global_load_dwordx4 v[144:147], v187, s[70:71]
	v_add_u32_e32 v187, 0x6000, v186
	global_load_dwordx4 v[156:159], v187, s[68:69]
	global_load_dwordx4 v[152:155], v187, s[70:71]
	v_ashrrev_i32_e32 v117, 31, v116
	s_branch .LBB0_643
	v_ashrrev_i32_e32 v4, 4, v171
	v_ashrrev_i32_e32 v5, 31, v4
	v_lshlrev_b64 v[4:5], 2, v[4:5]
	v_lshl_add_u64 v[6:7], v[0:1], 0, v[4:5]
	v_lshl_add_u64 v[4:5], v[2:3], 0, v[4:5]
	global_load_dword v132, v[6:7], off
	global_load_dword v133, v[6:7], off offset:512
	global_load_dword v134, v[6:7], off offset:1024
	global_load_dword v135, v[6:7], off offset:1536
	global_load_dword v128, v[4:5], off
	global_load_dword v129, v[4:5], off offset:512
	global_load_dword v130, v[4:5], off offset:1024
	global_load_dword v131, v[4:5], off offset:1536
	v_cndmask_b32_e64 v4, 0, 1, s[24:25]
	v_cmp_ne_u32_e64 s[0:1], 1, v4
	s_andn2_b64 vcc, exec, s[24:25]
	s_cbranch_vccz .LBB0_660

.LBB0_1353:
	s_cmp_lt_u32 s60, 0x80
	s_cselect_b32 s100, 2, 6
	v_cmp_eq_u32_e64 s[0:1], 0, v180
	s_and_saveexec_b64 s[2:3], s[0:1]
	s_cbranch_execz .Lpw_done1
	v_readlane_b32 s4, v254, 2
	v_readlane_b32 s5, v254, 3
	v_mov_b32_e32 v0, 0
	s_mov_b32 s12, 0
	s_min_u32 s14, s94, 0x100
	s_nop 4

.LBB0_1354:
	v_lshrrev_b32_e32 v1, 4, v171
	v_lshlrev_b32_e32 v6, 1, v120
	v_mul_lo_u32 v1, v1, s53
	v_and_b32_e32 v6, 0x78, v6
	v_add3_u32 v1, 0, v1, v6
	s_waitcnt lgkmcnt(0)
	s_barrier
	s_waitcnt vmcnt(6)
	v_cvt_pk_bf16_f32 v2, v132, v133
	s_waitcnt vmcnt(4)
	v_cvt_pk_bf16_f32 v3, v134, v135
	s_waitcnt vmcnt(2)
	v_cvt_pk_bf16_f32 v4, v128, v129
	s_waitcnt vmcnt(0)
	v_cvt_pk_bf16_f32 v5, v130, v131
	ds_write2_b64 v1, v[2:3], v[4:5] offset1:16
	v_lshrrev_b32_e32 v1, 4, v172
	v_mul_lo_u32 v1, v1, s53
	v_add3_u32 v1, 0, v1, v6
	v_cvt_pk_bf16_f32 v2, v140, v141
	v_cvt_pk_bf16_f32 v3, v142, v143
	v_cvt_pk_bf16_f32 v4, v136, v137
	v_cvt_pk_bf16_f32 v5, v138, v139
	ds_write2_b64 v1, v[2:3], v[4:5] offset1:16
	v_lshrrev_b32_e32 v1, 4, v173
	v_mul_lo_u32 v1, v1, s53
	v_add3_u32 v1, 0, v1, v6
	v_cvt_pk_bf16_f32 v2, v148, v149
	v_cvt_pk_bf16_f32 v3, v150, v151
	v_cvt_pk_bf16_f32 v4, v144, v145
	v_cvt_pk_bf16_f32 v5, v146, v147
	ds_write2_b64 v1, v[2:3], v[4:5] offset1:16
	v_lshrrev_b32_e32 v1, 4, v174
	v_mul_lo_u32 v1, v1, s53
	v_ashrrev_i32_e32 v22, 6, v171
	v_add3_u32 v1, 0, v1, v6
	v_cvt_pk_bf16_f32 v2, v156, v157
	v_cvt_pk_bf16_f32 v3, v158, v159
	v_cvt_pk_bf16_f32 v4, v152, v153
	v_cvt_pk_bf16_f32 v5, v154, v155
	ds_write2_b64 v1, v[2:3], v[4:5] offset1:16
	v_lshlrev_b32_e32 v1, 5, v22
	v_and_b32_e32 v0, 15, v171
	v_and_b32_e32 v23, 32, v1
	v_or_b32_e32 v2, v23, v0
	v_and_b32_e32 v26, 48, v171
	v_mul_u32_u24_e32 v2, 0x48, v2
	v_add_u32_e32 v24, s58, v26
	v_lshlrev_b32_e32 v14, 1, v2
	v_add_u32_e32 v10, v24, v14
	ds_read_b128 v[2:5], v10
	v_bfi_b32 v1, -16, v170, v171
	v_mul_lo_u32 v25, v1, s55
	v_add3_u32 v27, s57, v25, v26
	ds_read_b128 v[6:9], v27
	ds_read_b128 v[10:13], v10 offset:64
	v_add_u32_e32 v28, s56, v26
	v_add_u32_e32 v29, v28, v14
	ds_read_b128 v[14:17], v27 offset:64
	s_waitcnt lgkmcnt(2)
	v_mfma_f32_16x16x32_bf16 v[2:5], v[2:5], v[6:9], 0
	ds_read_b128 v[6:9], v29
	v_add3_u32 v30, s54, v25, v26
	ds_read_b128 v[18:21], v30
	s_waitcnt lgkmcnt(2)
	v_mfma_f32_16x16x32_bf16 v[2:5], v[10:13], v[14:17], v[2:5]
	ds_read_b128 v[10:13], v29 offset:64
	ds_read_b128 v[14:17], v30 offset:64
	v_bfe_u32 v29, v171, 4, 2
	s_waitcnt lgkmcnt(2)
	v_mfma_f32_16x16x32_bf16 v[6:9], v[6:9], v[18:21], 0
	v_lshlrev_b32_e32 v31, 2, v29
	v_add_u32_e32 v25, 0, v25
	v_lshlrev_b32_e32 v18, 3, v29
	s_waitcnt lgkmcnt(0)
	v_mfma_f32_16x16x32_bf16 v[6:9], v[10:13], v[14:17], v[6:9]
	v_or_b32_e32 v10, v23, v31
	v_cmp_le_i32_e32 vcc, v10, v1
	v_add_u32_e32 v47, 0, v26
	v_add_u32_e32 v34, v25, v26
	v_add_u32_e32 v48, s59, v26
	s_nop 2
	v_cndmask_b32_e32 v6, 0, v6, vcc
	v_cmp_lt_i32_e32 vcc, v10, v1
	s_movk_i32 s0, 0x2000
	s_add_i32 s29, s29, 1
	v_cndmask_b32_e64 v2, v2, 0, vcc
	v_add_f32_e32 v2, v2, v6
	v_or_b32_e32 v6, 1, v10
	v_cndmask_b32_e32 v7, 0, v7, vcc
	v_cmp_ge_i32_e32 vcc, v6, v1
	v_or_b32_e32 v6, 2, v10
	s_cmp_eq_u32 s29, s100
	v_cndmask_b32_e32 v3, 0, v3, vcc
	v_cmp_le_i32_e32 vcc, v6, v1
	v_add_f32_e32 v3, v3, v7
	v_cvt_pk_bf16_f32 v2, v2, v3
	s_nop 0
	v_cndmask_b32_e32 v7, 0, v8, vcc
	v_cmp_ge_i32_e32 vcc, v6, v1
	v_or_b32_e32 v6, 3, v10
	s_nop 0
	v_cndmask_b32_e32 v4, 0, v4, vcc
	v_cmp_le_i32_e32 vcc, v6, v1
	v_add_f32_e32 v4, v4, v7
	s_nop 0
	v_cndmask_b32_e32 v7, 0, v9, vcc
	v_cmp_ge_i32_e32 vcc, v6, v1
	s_nop 1
	v_cndmask_b32_e32 v5, 0, v5, vcc
	v_add_f32_e32 v5, v5, v7
	v_cvt_pk_bf16_f32 v3, v4, v5
	v_lshlrev_b32_e32 v4, 1, v23
	v_add3_u32 v29, v25, v18, v4
	v_or_b32_e32 v23, 16, v23
	ds_write_b64 v29, v[2:3] offset:36864
	v_or_b32_e32 v2, v23, v0
	v_mul_u32_u24_e32 v2, 0x48, v2
	v_lshlrev_b32_e32 v14, 1, v2
	v_add_u32_e32 v10, v24, v14
	ds_read_b128 v[2:5], v10
	ds_read_b128 v[6:9], v27
	ds_read_b128 v[10:13], v10 offset:64
	v_add_u32_e32 v18, v28, v14
	ds_read_b128 v[14:17], v27 offset:64
	s_waitcnt lgkmcnt(2)
	v_mfma_f32_16x16x32_bf16 v[2:5], v[2:5], v[6:9], 0
	ds_read_b128 v[6:9], v18
	ds_read_b128 v[18:21], v18 offset:64
	v_lshl_add_u32 v27, v1, 7, v34
	s_waitcnt lgkmcnt(2)
	v_mfma_f32_16x16x32_bf16 v[2:5], v[10:13], v[14:17], v[2:5]
	ds_read_b128 v[10:13], v30
	ds_read_b128 v[14:17], v30 offset:64
	s_waitcnt lgkmcnt(1)
	v_mfma_f32_16x16x32_bf16 v[6:9], v[6:9], v[10:13], 0
	v_or_b32_e32 v10, v23, v31
	v_cmp_le_i32_e32 vcc, v10, v1
	s_waitcnt lgkmcnt(0)
	v_mfma_f32_16x16x32_bf16 v[6:9], v[18:21], v[14:17], v[6:9]
	s_nop 7
	v_cndmask_b32_e32 v6, 0, v6, vcc
	v_cmp_lt_i32_e32 vcc, v10, v1
	s_nop 1
	v_cndmask_b32_e64 v2, v2, 0, vcc
	v_add_f32_e32 v2, v2, v6
	v_or_b32_e32 v6, 1, v10
	v_cndmask_b32_e32 v7, 0, v7, vcc
	v_cmp_ge_i32_e32 vcc, v6, v1
	v_or_b32_e32 v6, 2, v10
	s_nop 0
	v_cndmask_b32_e32 v3, 0, v3, vcc
	v_cmp_le_i32_e32 vcc, v6, v1
	v_add_f32_e32 v3, v3, v7
	v_cvt_pk_bf16_f32 v2, v2, v3
	s_nop 0
	v_cndmask_b32_e32 v7, 0, v8, vcc
	v_cmp_ge_i32_e32 vcc, v6, v1
	v_or_b32_e32 v6, 3, v10
	s_nop 0
	v_cndmask_b32_e32 v4, 0, v4, vcc
	v_cmp_le_i32_e32 vcc, v6, v1
	v_add_f32_e32 v4, v4, v7
	s_nop 0
	v_cndmask_b32_e32 v7, 0, v9, vcc
	v_cmp_ge_i32_e32 vcc, v6, v1
	s_nop 1
	v_cndmask_b32_e32 v5, 0, v5, vcc
	v_add_f32_e32 v5, v5, v7
	v_cvt_pk_bf16_f32 v3, v4, v5
	ds_write_b64 v29, v[2:3] offset:36896
	v_lshlrev_b32_e32 v2, 2, v22
	v_and_b32_e32 v46, 4, v2
	v_lshl_or_b32 v30, v46, 4, v0
	v_mad_u32_u24 v22, v30, s53, v47
	s_waitcnt lgkmcnt(0)
	s_barrier
	ds_read_b128 v[2:5], v22
	ds_read_b128 v[6:9], v22 offset:64
	ds_read_b128 v[10:13], v27 offset:54272
	ds_read_b128 v[14:17], v27 offset:54336
	ds_read_b128 v[18:21], v22 offset:128
	s_waitcnt lgkmcnt(2)
	v_mfma_f32_16x16x32_bf16 v[2:5], v[2:5], v[10:13], 0
	v_mad_u32_u24 v30, v30, s55, v48
	v_or_b32_e32 v49, 1, v46
	v_lshl_or_b32 v42, v49, 4, v0
	s_waitcnt lgkmcnt(1)
	v_mfma_f32_16x16x32_bf16 v[2:5], v[6:9], v[14:17], v[2:5]
	ds_read_b128 v[6:9], v27 offset:54400
	ds_read_b128 v[22:25], v22 offset:192
	ds_read_b128 v[26:29], v27 offset:54464
	v_mad_u32_u24 v43, v42, s53, v47
	s_waitcnt lgkmcnt(2)
	v_mfma_f32_16x16x32_bf16 v[2:5], v[18:21], v[6:9], v[2:5]
	ds_read_b128 v[18:21], v30
	v_or_b32_e32 v50, 2, v46
	v_lshl_or_b32 v51, v50, 4, v0
	s_waitcnt lgkmcnt(1)
	v_mfma_f32_16x16x32_bf16 v[2:5], v[22:25], v[26:29], v[2:5]
	ds_read_b128 v[22:25], v34 offset:36864
	ds_read_b128 v[30:33], v30 offset:64
	ds_read_b128 v[34:37], v34 offset:36928
	ds_read_b128 v[38:41], v43 offset:128
	v_mad_u32_u24 v52, v51, s53, v47
	s_waitcnt lgkmcnt(3)
	v_mfma_f32_16x16x32_bf16 v[2:5], v[18:21], v[22:25], v[2:5]
	ds_read_b128 v[18:21], v43
	s_waitcnt lgkmcnt(2)
	v_mfma_f32_16x16x32_bf16 v[2:5], v[30:33], v[34:37], v[2:5]
	ds_read_b128 v[30:33], v43 offset:64
	s_waitcnt lgkmcnt(1)
	v_mfma_f32_16x16x32_bf16 v[18:21], v[18:21], v[10:13], 0
	s_waitcnt lgkmcnt(0)
	v_mfma_f32_16x16x32_bf16 v[18:21], v[30:33], v[14:17], v[18:21]
	ds_read_b128 v[30:33], v43 offset:192
	v_mfma_f32_16x16x32_bf16 v[18:21], v[38:41], v[6:9], v[18:21]
	v_mad_u32_u24 v38, v42, s55, v48
	s_waitcnt lgkmcnt(0)
	v_mfma_f32_16x16x32_bf16 v[18:21], v[30:33], v[26:29], v[18:21]
	ds_read_b128 v[30:33], v38
	ds_read_b128 v[38:41], v38 offset:64
	ds_read_b128 v[42:45], v52 offset:128
	s_waitcnt lgkmcnt(2)
	v_mfma_f32_16x16x32_bf16 v[18:21], v[30:33], v[22:25], v[18:21]
	ds_read_b128 v[30:33], v52
	s_waitcnt lgkmcnt(2)
	v_mfma_f32_16x16x32_bf16 v[18:21], v[38:41], v[34:37], v[18:21]
	ds_read_b128 v[38:41], v52 offset:64
	s_waitcnt lgkmcnt(1)
	v_mfma_f32_16x16x32_bf16 v[30:33], v[30:33], v[10:13], 0
	s_waitcnt lgkmcnt(0)
	v_mfma_f32_16x16x32_bf16 v[30:33], v[38:41], v[14:17], v[30:33]
	ds_read_b128 v[38:41], v52 offset:192
	v_mfma_f32_16x16x32_bf16 v[30:33], v[42:45], v[6:9], v[30:33]
	v_mad_u32_u24 v42, v51, s55, v48
	v_or_b32_e32 v51, 3, v46
	v_lshl_or_b32 v0, v51, 4, v0
	s_waitcnt lgkmcnt(0)
	v_mfma_f32_16x16x32_bf16 v[30:33], v[38:41], v[26:29], v[30:33]
	ds_read_b128 v[38:41], v42
	ds_read_b128 v[42:45], v42 offset:64
	v_mad_u32_u24 v52, v0, s53, v47
	v_mad_u32_u24 v0, v0, s55, v48
	s_waitcnt lgkmcnt(1)
	v_mfma_f32_16x16x32_bf16 v[30:33], v[38:41], v[22:25], v[30:33]
	ds_read_b128 v[38:41], v52
	s_waitcnt lgkmcnt(1)
	v_mfma_f32_16x16x32_bf16 v[30:33], v[42:45], v[34:37], v[30:33]
	ds_read_b128 v[42:45], v52 offset:64
	s_waitcnt lgkmcnt(1)
	v_mfma_f32_16x16x32_bf16 v[10:13], v[38:41], v[10:13], 0
	ds_read_b128 v[38:41], v52 offset:128
	s_waitcnt lgkmcnt(1)
	v_mfma_f32_16x16x32_bf16 v[10:13], v[42:45], v[14:17], v[10:13]
	ds_read_b128 v[14:17], v52 offset:192
	s_waitcnt lgkmcnt(1)
	v_mfma_f32_16x16x32_bf16 v[6:9], v[38:41], v[6:9], v[10:13]
	s_nop 4
	ds_read_b128 v[10:13], v0
	s_waitcnt lgkmcnt(1)
	v_mfma_f32_16x16x32_bf16 v[6:9], v[14:17], v[26:29], v[6:9]
	ds_read_b128 v[14:17], v0 offset:64
	v_lshl_add_u32 v0, v1, 9, v47
	v_lshl_add_u32 v1, v46, 6, v0
	s_waitcnt lgkmcnt(1)
	v_mfma_f32_16x16x32_bf16 v[6:9], v[10:13], v[22:25], v[6:9]
	s_waitcnt lgkmcnt(0)
	s_barrier
	v_mfma_f32_16x16x32_bf16 v[6:9], v[14:17], v[34:37], v[6:9]
	ds_write_b128 v1, v[2:5] offset:54272
	v_lshl_add_u32 v1, v49, 6, v0
	ds_write_b128 v1, v[18:21] offset:54272
	v_lshl_add_u32 v1, v50, 6, v0
	v_lshl_add_u32 v0, v51, 6, v0
	ds_write_b128 v1, v[30:33] offset:54272
	s_nop 1
	ds_write_b128 v0, v[6:9] offset:54272
	v_lshlrev_b32_e32 v16, 2, v176
	v_lshl_add_u64 v[0:1], v[118:119], 0, s[8:9]
	v_lshlrev_b32_e32 v176, 1, v176
	v_lshl_add_u64 v[0:1], v[0:1], 0, v[176:177]
	v_add_co_u32_e32 v2, vcc, s0, v0
	s_mov_b64 s[0:1], 0x2000
	s_nop 0
	v_addc_co_u32_e32 v3, vcc, 0, v1, vcc
	v_lshl_add_u64 v[0:1], v[0:1], 0, s[0:1]
	s_waitcnt lgkmcnt(0)
	s_barrier
	global_load_dwordx4 v[38:41], v[2:3], off
	global_load_dwordx4 v[28:31], v[0:1], off offset:16
	v_lshlrev_b32_e32 v2, 9, v170
	v_add3_u32 v2, 0, v2, v16
	ds_read_b128 v[24:27], v2 offset:54272
	ds_read_b128 v[12:15], v2 offset:54288
	ds_read_b128 v[4:7], v2 offset:54304
	ds_read_b128 v[0:3], v2 offset:54320
	global_load_dwordx4 v[32:35], v16, s[30:31] offset:512
	global_load_dwordx4 v[20:23], v16, s[30:31] offset:528
	s_waitcnt lgkmcnt(3)
	v_mul_f32_e32 v10, v25, v25
	v_fmac_f32_e32 v10, v24, v24
	v_fmac_f32_e32 v10, v26, v26
	v_fmac_f32_e32 v10, v27, v27
	s_waitcnt lgkmcnt(2)
	v_fmac_f32_e32 v10, v12, v12
	v_fmac_f32_e32 v10, v13, v13
	v_fmac_f32_e32 v10, v14, v14
	v_fmac_f32_e32 v10, v15, v15
	s_waitcnt lgkmcnt(1)
	v_pk_mul_f32 v[8:9], v[4:5], v[4:5]
	s_mov_b32 s0, 0x800000
	v_add_f32_e32 v8, v10, v8
	v_add_f32_e32 v10, v8, v9
	v_pk_mul_f32 v[8:9], v[6:7], v[6:7]
	s_waitcnt vmcnt(3)
	v_and_b32_e32 v47, 0xffff0000, v40
	v_add_f32_e32 v8, v10, v8
	v_add_f32_e32 v10, v8, v9
	s_waitcnt lgkmcnt(0)
	v_pk_mul_f32 v[8:9], v[0:1], v[0:1]
	v_lshlrev_b32_e32 v48, 16, v41
	v_add_f32_e32 v8, v10, v8
	v_add_f32_e32 v10, v8, v9
	v_pk_mul_f32 v[8:9], v[2:3], v[2:3]
	v_and_b32_e32 v49, 0xffff0000, v41
	v_add_f32_e32 v8, v10, v8
	v_and_b32_e32 v10, 64, v183
	v_add_f32_e32 v8, v8, v9
	v_xor_b32_e32 v9, 1, v183
	v_add_u32_e32 v10, 64, v10
	v_cmp_lt_i32_e32 vcc, v9, v10
	s_waitcnt vmcnt(2)
	v_lshlrev_b32_e32 v41, 16, v28
	v_lshlrev_b32_e32 v44, 16, v39
	v_cndmask_b32_e32 v9, v183, v9, vcc
	v_lshlrev_b32_e32 v9, 2, v9
	ds_bpermute_b32 v9, v9, v8
	v_and_b32_e32 v45, 0xffff0000, v39
	v_and_b32_e32 v39, 0xffff0000, v28
	v_lshlrev_b32_e32 v42, 16, v38
	v_and_b32_e32 v43, 0xffff0000, v38
	s_waitcnt lgkmcnt(0)
	v_add_f32_e32 v8, v8, v9
	v_xor_b32_e32 v9, 2, v183
	v_cmp_lt_i32_e32 vcc, v9, v10
	v_lshlrev_b32_e32 v38, 16, v29
	v_and_b32_e32 v37, 0xffff0000, v29
	v_cndmask_b32_e32 v9, v183, v9, vcc
	v_lshlrev_b32_e32 v9, 2, v9
	ds_bpermute_b32 v9, v9, v8
	v_lshlrev_b32_e32 v29, 16, v30
	v_and_b32_e32 v28, 0xffff0000, v30
	v_mul_f32_e32 v30, 0xbfb8aa3b, v42
	v_exp_f32_e32 v50, v30
	s_waitcnt lgkmcnt(0)
	v_add_f32_e32 v8, v8, v9
	v_xor_b32_e32 v9, 4, v183
	v_cmp_lt_i32_e32 vcc, v9, v10
	v_lshlrev_b32_e32 v46, 16, v40
	v_lshlrev_b32_e32 v40, 16, v31
	v_cndmask_b32_e32 v9, v183, v9, vcc
	v_lshlrev_b32_e32 v9, 2, v9
	ds_bpermute_b32 v9, v9, v8
	v_and_b32_e32 v30, 0xffff0000, v31
	v_add_f32_e32 v31, 1.0, v50
	v_rcp_f32_e32 v31, v31
	s_waitcnt lgkmcnt(0)
	v_add_f32_e32 v8, v8, v9
	v_fmamk_f32 v8, v8, 0x3c000000, v184
	v_mul_f32_e32 v9, 0x4b800000, v8
	v_cmp_gt_f32_e32 vcc, s0, v8
	v_mul_f32_e32 v31, v31, v42
	s_nop 0
	v_cndmask_b32_e32 v8, v8, v9, vcc
	v_rsq_f32_e32 v8, v8
	s_nop 0
	v_mul_f32_e32 v9, 0x45800000, v8
	v_cndmask_b32_e32 v36, v8, v9, vcc
	global_load_dwordx4 v[8:11], v16, s[30:31] offset:560
	s_nop 0
	global_load_dwordx4 v[16:19], v16, s[30:31] offset:544
	v_mul_f32_e32 v12, v12, v36
	s_waitcnt vmcnt(2)
	v_mul_f32_e32 v12, v12, v20
	v_mul_f32_e32 v20, 0xbfb8aa3b, v47
	v_exp_f32_e32 v20, v20
	v_mul_f32_e32 v13, v13, v36
	v_mul_f32_e32 v13, v13, v21
	v_mul_f32_e32 v21, 0xbfb8aa3b, v48
	v_add_f32_e32 v20, 1.0, v20
	v_rcp_f32_e32 v20, v20
	v_exp_f32_e32 v21, v21
	v_mul_f32_e32 v14, v14, v36
	v_mul_f32_e32 v14, v14, v22
	v_mul_f32_e32 v20, v20, v47
	v_mul_f32_e32 v13, v20, v13
	v_add_f32_e32 v20, 1.0, v21
	v_rcp_f32_e32 v20, v20
	v_mul_f32_e32 v21, 0xbfb8aa3b, v49
	v_exp_f32_e32 v21, v21
	v_mul_f32_e32 v15, v15, v36
	v_mul_f32_e32 v20, v20, v48
	v_mul_f32_e32 v14, v20, v14
	v_add_f32_e32 v20, 1.0, v21
	v_rcp_f32_e32 v20, v20
	v_mul_f32_e32 v21, 0xbfb8aa3b, v41
	v_exp_f32_e32 v21, v21
	v_mul_f32_e32 v15, v15, v23
	v_mul_f32_e32 v20, v20, v49
	v_mul_f32_e32 v15, v20, v15
	v_mul_f32_e32 v4, v4, v36
	v_add_f32_e32 v20, 1.0, v21
	v_rcp_f32_e32 v20, v20
	v_mul_f32_e32 v24, v24, v36
	v_mul_f32_e32 v24, v32, v24
	v_mul_f32_e32 v32, 0xbfb8aa3b, v43
	v_mul_f32_e32 v20, v20, v41
	v_exp_f32_e32 v32, v32
	v_mul_f32_e32 v24, v31, v24
	v_mul_f32_e32 v0, v0, v36
	v_mul_f32_e32 v25, v25, v36
	v_add_f32_e32 v31, 1.0, v32
	v_rcp_f32_e32 v31, v31
	v_mul_f32_e32 v32, 0xbfb8aa3b, v44
	v_exp_f32_e32 v32, v32
	v_mul_f32_e32 v25, v25, v33
	v_mul_f32_e32 v31, v31, v43
	v_mul_f32_e32 v25, v31, v25
	v_add_f32_e32 v31, 1.0, v32
	v_rcp_f32_e32 v31, v31
	v_mul_f32_e32 v32, 0xbfb8aa3b, v45
	v_exp_f32_e32 v32, v32
	v_mul_f32_e32 v26, v26, v36
	v_mul_f32_e32 v26, v26, v34
	v_mul_f32_e32 v31, v31, v44
	v_mul_f32_e32 v26, v31, v26
	v_add_f32_e32 v31, 1.0, v32
	v_rcp_f32_e32 v31, v31
	v_mul_f32_e32 v32, 0xbfb8aa3b, v46
	v_exp_f32_e32 v32, v32
	v_mul_f32_e32 v27, v27, v36
	v_mul_f32_e32 v27, v27, v35
	v_mul_f32_e32 v31, v31, v45
	v_mul_f32_e32 v27, v31, v27
	v_add_f32_e32 v31, 1.0, v32
	v_mul_f32_e32 v2, v2, v36
	v_rcp_f32_e32 v31, v31
	s_waitcnt vmcnt(1)
	v_mul_f32_e32 v0, v0, v8
	s_waitcnt vmcnt(0)
	v_mul_f32_e32 v4, v4, v16
	v_mul_f32_e32 v16, 0xbfb8aa3b, v39
	v_exp_f32_e32 v16, v16
	v_mul_f32_e32 v20, v20, v4
	v_mul_f32_e32 v4, v5, v36
	v_mul_f32_e32 v4, v4, v17
	v_add_f32_e32 v5, 1.0, v16
	v_rcp_f32_e32 v5, v5
	v_mul_f32_e32 v16, 0xbfb8aa3b, v38
	v_exp_f32_e32 v16, v16
	v_mul_f32_e32 v2, v2, v10
	v_mul_f32_e32 v5, v5, v39
	v_mul_f32_e32 v17, v5, v4
	v_add_f32_e32 v5, 1.0, v16
	v_mul_f32_e32 v4, v6, v36
	v_rcp_f32_e32 v5, v5
	v_mul_f32_e32 v6, 0xbfb8aa3b, v37
	v_exp_f32_e32 v6, v6
	v_mul_f32_e32 v4, v4, v18
	v_mul_f32_e32 v5, v5, v38
	v_mul_f32_e32 v16, v5, v4
	v_add_f32_e32 v5, 1.0, v6
	v_rcp_f32_e32 v5, v5
	v_mul_f32_e32 v6, 0xbfb8aa3b, v29
	v_exp_f32_e32 v6, v6
	v_mul_f32_e32 v4, v7, v36
	v_mul_f32_e32 v4, v4, v19
	v_mul_f32_e32 v5, v5, v37
	v_mul_f32_e32 v7, v5, v4
	v_add_f32_e32 v4, 1.0, v6
	v_rcp_f32_e32 v4, v4
	v_mul_f32_e32 v5, 0xbfb8aa3b, v28
	v_exp_f32_e32 v5, v5
	v_mul_f32_e32 v31, v31, v46
	v_mul_f32_e32 v4, v4, v29
	v_mul_f32_e32 v6, v4, v0
	v_mul_f32_e32 v0, v1, v36
	v_add_f32_e32 v1, 1.0, v5
	v_rcp_f32_e32 v1, v1
	v_mul_f32_e32 v4, 0xbfb8aa3b, v40
	v_exp_f32_e32 v4, v4
	v_mul_f32_e32 v0, v0, v9
	v_mul_f32_e32 v1, v1, v28
	v_mul_f32_e32 v8, v1, v0
	v_mul_f32_e32 v1, 0xbfb8aa3b, v30
	v_exp_f32_e32 v1, v1
	v_add_f32_e32 v0, 1.0, v4
	v_rcp_f32_e32 v0, v0
	v_mul_f32_e32 v12, v31, v12
	v_add_f32_e32 v1, 1.0, v1
	v_rcp_f32_e32 v1, v1
	v_mul_f32_e32 v0, v0, v40
	v_mul_f32_e32 v9, v0, v2
	v_mul_f32_e32 v0, v3, v36
	v_mul_f32_e32 v0, v0, v11
	v_mul_f32_e32 v1, v1, v30
	v_mul_f32_e32 v10, v1, v0
	v_lshlrev_b64 v[0:1], 13, v[116:117]
	v_lshl_add_u64 v[0:1], s[4:5], 0, v[0:1]
	v_lshl_add_u64 v[4:5], v[0:1], 0, v[176:177]
	v_cvt_pk_bf16_f32 v0, v24, v25
	v_cvt_pk_bf16_f32 v1, v26, v27
	v_cvt_pk_bf16_f32 v2, v12, v13
	v_cvt_pk_bf16_f32 v3, v14, v15
	global_store_dwordx4 v[4:5], v[0:3], off offset:2048
	s_nop 1
	v_cvt_pk_bf16_f32 v0, v20, v17
	v_cvt_pk_bf16_f32 v1, v16, v7
	v_cvt_pk_bf16_f32 v2, v6, v8
	v_cvt_pk_bf16_f32 v3, v9, v10
	global_store_dwordx4 v[4:5], v[0:3], off offset:2064
	s_barrier
	s_cbranch_scc1 .LBB0_1304
.LBB0_1355:
	s_lshr_b32 s0, s60, 3
	s_cmp_lt_u32 s60, 0x80
	s_cbranch_scc1 .Lgrebb
	s_add_i32 s0, s0, 16
.Lgrebb:
	s_lshl_b32 s12, s29, 4
	s_add_i32 s0, s0, s12
	s_lshl_b32 s0, s0, 3
	s_and_b32 s12, s60, 7
	s_or_b32 s12, s0, s12
	s_mul_i32 s0, s12, 0x8200
	v_mov_b32_e32 v171, v180
	s_mul_hi_i32 s1, s12, 0x8200
	s_add_u32 s0, s46, s0
	s_movk_i32 s2, 0x820
	s_addc_u32 s1, s47, s1
	v_lshlrev_b32_e32 v120, 2, v171
	v_lshlrev_b32_e32 v186, 4, v171
	v_ashrrev_i32_e32 v121, 31, v120
	global_load_dwordx4 v[188:191], v186, s[0:1]
	v_add_u32_e32 v172, 0x200, v171
	v_add_u32_e32 v187, 0x2000, v186
	v_lshlrev_b32_e32 v126, 2, v172
	global_load_dwordx4 v[192:195], v187, s[0:1]
	v_add_u32_e32 v173, 0x400, v171
	v_add_u32_e32 v187, 0x4000, v186
	v_lshlrev_b32_e32 v124, 2, v173
	global_load_dwordx4 v[196:199], v187, s[0:1]
	v_add_u32_e32 v174, 0x600, v171
	v_add_u32_e32 v187, 0x6000, v186
	v_lshlrev_b32_e32 v122, 2, v174
	global_load_dwordx4 v[200:203], v187, s[0:1]
	v_cmp_gt_i32_e32 vcc, 32, v171
	v_add_u32_e32 v187, 0x8000, v186
	s_nop 1
	v_cndmask_b32_e32 v187, 0, v187, vcc
	global_load_dwordx4 v[204:207], v187, s[0:1]
	s_ashr_i32 s61, s12, 3
	v_readlane_b32 s64, v254, 12
	s_lshl_b32 s0, s61, 6
	v_ashrrev_i32_e32 v170, 3, v171
	v_readlane_b32 s70, v254, 18
	v_readlane_b32 s71, v254, 19
	v_add_u32_e32 v116, s0, v170
	v_and_b32_e32 v19, 7, v171
	v_mov_b64_e32 v[0:1], s[70:71]
	v_mad_i64_i32 v[118:119], s[2:3], v116, s52, v[0:1]
	s_mov_b32 s7, s9
	v_lshl_add_u64 v[0:1], v[118:119], 0, s[6:7]
	v_lshlrev_b32_e32 v176, 4, v19
	v_lshl_add_u64 v[0:1], v[0:1], 0, v[176:177]
	v_add_co_u32_e32 v0, vcc, s34, v0
	s_nop 1
	v_addc_co_u32_e32 v1, vcc, 0, v1, vcc
	global_load_dwordx4 v[4:7], v[0:1], off
	global_load_dwordx4 v[8:11], v[0:1], off offset:1024
	s_waitcnt vmcnt(2)
	ds_write_b128 v186, v[188:191]
	ds_write_b128 v186, v[192:195] offset:8192
	ds_write_b128 v186, v[196:199] offset:16384
	ds_write_b128 v186, v[200:203] offset:24576
	v_cmp_gt_i32_e64 s[98:99], 32, v171
	s_and_saveexec_b64 s[62:63], s[98:99]
	ds_write_b128 v186, v[204:207] offset:32768
	s_mov_b64 exec, s[62:63]
	s_waitcnt lgkmcnt(0)
	s_barrier
	v_lshlrev_b32_e32 v16, 5, v19
	v_add_u32_e32 v18, 0, v16
	ds_read_b128 v[12:15], v18 offset:8320
	ds_read_b128 v[0:3], v18 offset:8336
	s_movk_i32 s1, 0x104
	v_mad_u64_u32 v[20:21], s[2:3], v170, s1, v[18:19]
	v_add_u32_e32 v21, 0x6084, v18
	v_add_u32_e32 v17, 0x607c, v18
	v_add_u32_e32 v30, 0x4100, v20
	v_add_u32_e32 v31, 0x4108, v20
	ds_read2_b32 v[28:29], v20 offset1:1
	ds_read2_b32 v[26:27], v20 offset0:2 offset1:3
	ds_read2_b32 v[24:25], v20 offset0:4 offset1:5
	ds_read2_b32 v[22:23], v20 offset0:6 offset1:7
	ds_read2_b32 v[32:33], v30 offset1:1
	ds_read2_b32 v[34:35], v17 offset1:1
	ds_read2_b32 v[40:41], v31 offset1:1
	ds_read2_b32 v[42:43], v21 offset1:1
	s_waitcnt lgkmcnt(7)
	v_sub_f32_e32 v21, v28, v12
	v_sub_f32_e32 v12, v12, v28
	v_mul_f32_e32 v12, 0x3fb8aa3b, v12
	v_exp_f32_e32 v12, v12
	v_mul_f32_e32 v17, 0x3fb8aa3b, v28
	v_mul_f32_e32 v28, 0x3fb8aa3b, v29
	v_sub_f32_e32 v30, v29, v13
	v_sub_f32_e32 v37, v13, v29
	v_exp_f32_e32 v13, v17
	s_waitcnt lgkmcnt(3)
	v_mul_f32_e32 v17, 0x3fb8aa3b, v32
	s_waitcnt lgkmcnt(2)
	v_sub_f32_e32 v29, v32, v34
	v_sub_f32_e32 v31, v34, v32
	v_exp_f32_e32 v32, v28
	v_mul_f32_e32 v21, 0x3fb8aa3b, v21
	v_mul_f32_e32 v30, 0x3fb8aa3b, v30
	v_mul_f32_e32 v29, 0x3fb8aa3b, v29
	v_mul_f32_e32 v31, 0x3fb8aa3b, v31
	v_exp_f32_e32 v21, v21
	v_exp_f32_e32 v30, v30
	v_exp_f32_e32 v38, v29
	v_exp_f32_e32 v29, v31
	v_mul_f32_e32 v28, 0x3fb8aa3b, v33
	v_exp_f32_e32 v17, v17
	v_exp_f32_e32 v34, v28
	s_mov_b64 s[2:3], 0x1800
	s_cmp_lt_i32 s61, 64
	s_mov_b32 s17, s9
	s_mov_b32 s15, s9
	v_readlane_b32 s65, v254, 13
	v_readlane_b32 s66, v254, 14
	v_readlane_b32 s67, v254, 15
	v_readlane_b32 s68, v254, 16
	v_readlane_b32 s69, v254, 17
	v_readlane_b32 s72, v254, 20
	v_readlane_b32 s73, v254, 21
	v_readlane_b32 s74, v254, 22
	v_readlane_b32 s75, v254, 23
	v_readlane_b32 s76, v254, 24
	v_readlane_b32 s77, v254, 25
	v_readlane_b32 s78, v254, 26
	v_readlane_b32 s79, v254, 27
	s_waitcnt vmcnt(1)
	v_lshlrev_b32_e32 v46, 16, v6
	v_and_b32_e32 v47, 0xffff0000, v6
	s_waitcnt vmcnt(0)
	v_lshlrev_b32_e32 v6, 16, v8
	v_lshlrev_b32_e32 v31, 16, v4
	v_and_b32_e32 v4, 0xffff0000, v4
	v_and_b32_e32 v45, 0xffff0000, v8
	v_mul_f32_e32 v8, v12, v6
	v_sub_f32_e32 v12, v35, v33
	v_lshlrev_b32_e32 v49, 16, v9
	v_and_b32_e32 v50, 0xffff0000, v9
	v_mul_f32_e32 v4, 0x3e000000, v4
	v_mul_f32_e32 v9, 0x3fb8aa3b, v37
	v_mul_f32_e32 v12, 0x3fb8aa3b, v12
	v_lshlrev_b32_e32 v48, 16, v7
	v_and_b32_e32 v36, 0xffff0000, v7
	v_lshlrev_b32_e32 v51, 16, v10
	v_and_b32_e32 v52, 0xffff0000, v10
	v_mul_f32_e32 v7, 0x3e000000, v31
	v_mul_f32_e32 v31, v4, v32
	v_exp_f32_e32 v9, v9
	v_sub_f32_e32 v10, v33, v35
	v_exp_f32_e32 v32, v12
	v_mul_f32_e32 v10, 0x3fb8aa3b, v10
	v_sub_f32_e32 v33, v26, v14
	v_sub_f32_e32 v14, v14, v26
	v_lshlrev_b32_e32 v39, 16, v11
	v_and_b32_e32 v28, 0xffff0000, v11
	v_mul_f32_e32 v11, v7, v21
	v_exp_f32_e32 v10, v10
	v_mul_f32_e32 v21, v4, v30
	v_mul_f32_e32 v30, 0x3fb8aa3b, v26
	v_mul_f32_e32 v14, 0x3fb8aa3b, v14
	v_exp_f32_e32 v30, v30
	v_exp_f32_e32 v14, v14
	v_mul_f32_e32 v12, v9, v45
	v_mul_f32_e32 v9, v32, v45
	s_waitcnt lgkmcnt(1)
	v_mul_f32_e32 v32, 0x3fb8aa3b, v40
	v_mul_f32_e32 v33, 0x3fb8aa3b, v33
	v_lshlrev_b32_e32 v44, 16, v5
	v_exp_f32_e32 v32, v32
	v_exp_f32_e32 v35, v33
	v_mul_f32_e32 v6, v29, v6
	v_mul_f32_e32 v29, v7, v13
	v_mul_f32_e32 v13, v7, v17
	v_mul_f32_e32 v17, v4, v34
	v_mul_f32_e32 v10, v4, v10
	v_mul_f32_e32 v4, 0x3e000000, v44
	v_mul_f32_e32 v34, v4, v30
	v_mul_f32_e32 v30, v14, v49
	s_waitcnt lgkmcnt(0)
	v_sub_f32_e32 v14, v40, v42
	v_sub_f32_e32 v26, v42, v40
	v_mul_f32_e32 v14, 0x3fb8aa3b, v14
	v_mul_f32_e32 v26, 0x3fb8aa3b, v26
	v_mul_f32_e32 v33, v4, v32
	v_mul_f32_e32 v32, v4, v35
	v_exp_f32_e32 v14, v14
	v_exp_f32_e32 v35, v26
	v_mul_f32_e32 v26, 0x3fb8aa3b, v27
	v_and_b32_e32 v5, 0xffff0000, v5
	v_exp_f32_e32 v37, v26
	v_mul_f32_e32 v26, v4, v14
	v_mul_f32_e32 v14, v35, v49
	v_sub_f32_e32 v35, v27, v15
	v_sub_f32_e32 v15, v15, v27
	v_sub_f32_e32 v27, v41, v43
	v_mul_f32_e32 v4, 0x3e000000, v5
	v_mul_f32_e32 v5, 0x3fb8aa3b, v41
	v_mul_f32_e32 v35, 0x3fb8aa3b, v35
	v_mul_f32_e32 v15, 0x3fb8aa3b, v15
	v_mul_f32_e32 v27, 0x3fb8aa3b, v27
	v_exp_f32_e32 v5, v5
	v_exp_f32_e32 v35, v35
	v_exp_f32_e32 v15, v15
	v_exp_f32_e32 v40, v27
	v_mul_f32_e32 v7, v7, v38
	v_mul_f32_e32 v37, v4, v37
	v_mul_f32_e32 v38, v4, v5
	v_mul_f32_e32 v35, v4, v35
	v_mul_f32_e32 v27, v15, v50
	v_mul_f32_e32 v15, v4, v40
	v_sub_f32_e32 v4, v43, v41
	v_mul_f32_e32 v4, 0x3fb8aa3b, v4
	v_exp_f32_e32 v49, v4
	v_add_u32_e32 v4, 0x4110, v20
	ds_read2_b32 v[4:5], v4 offset1:1
	v_add_u32_e32 v40, 0x608c, v18
	v_mul_f32_e32 v41, 0x3fb8aa3b, v24
	v_exp_f32_e32 v53, v41
	v_add_u32_e32 v20, 0x4118, v20
	v_add_u32_e32 v18, 0x6094, v18
	ds_read2_b32 v[40:41], v40 offset1:1
	ds_read2_b32 v[42:43], v20 offset1:1
	ds_read2_b32 v[44:45], v18 offset1:1
	s_waitcnt lgkmcnt(3)
	v_mul_f32_e32 v18, 0x3fb8aa3b, v4
	v_mul_f32_e32 v20, v49, v50
	v_sub_f32_e32 v50, v24, v0
	v_sub_f32_e32 v0, v0, v24
	s_waitcnt lgkmcnt(2)
	v_sub_f32_e32 v24, v4, v40
	v_sub_f32_e32 v4, v40, v4
	v_mul_f32_e32 v50, 0x3fb8aa3b, v50
	v_mul_f32_e32 v0, 0x3fb8aa3b, v0
	v_mul_f32_e32 v4, 0x3fb8aa3b, v4
	v_exp_f32_e32 v50, v50
	v_exp_f32_e32 v0, v0
	v_mul_f32_e32 v24, 0x3fb8aa3b, v24
	v_exp_f32_e32 v4, v4
	v_exp_f32_e32 v18, v18
	v_exp_f32_e32 v24, v24
	v_mul_f32_e32 v46, 0x3e000000, v46
	v_mul_f32_e32 v40, v46, v50
	v_mul_f32_e32 v50, v0, v51
	v_mul_f32_e32 v4, v4, v51
	v_sub_f32_e32 v51, v25, v1
	v_sub_f32_e32 v1, v1, v25
	v_mul_f32_e32 v49, v46, v53
	v_mul_f32_e32 v18, v46, v18
	v_mul_f32_e32 v24, v46, v24
	v_mul_f32_e32 v0, 0x3e000000, v47
	v_mul_f32_e32 v46, 0x3fb8aa3b, v25
	v_mul_f32_e32 v47, 0x3fb8aa3b, v5
	v_mul_f32_e32 v51, 0x3fb8aa3b, v51
	v_mul_f32_e32 v1, 0x3fb8aa3b, v1
	v_exp_f32_e32 v46, v46
	v_exp_f32_e32 v47, v47
	v_exp_f32_e32 v51, v51
	v_exp_f32_e32 v1, v1
	v_mul_f32_e32 v25, v0, v46
	v_mul_f32_e32 v46, v0, v47
	v_mul_f32_e32 v47, v0, v51
	v_mul_f32_e32 v51, v1, v52
	v_sub_f32_e32 v1, v5, v41
	v_mul_f32_e32 v1, 0x3fb8aa3b, v1
	v_exp_f32_e32 v1, v1
	v_sub_f32_e32 v5, v41, v5
	v_mul_f32_e32 v41, 0x3fb8aa3b, v22
	v_mul_f32_e32 v5, 0x3fb8aa3b, v5
	v_mul_f32_e32 v53, v0, v1
	v_mul_f32_e32 v0, 0x3e000000, v48
	v_sub_f32_e32 v48, v22, v2
	v_sub_f32_e32 v2, v2, v22
	s_waitcnt lgkmcnt(0)
	v_sub_f32_e32 v22, v42, v44
	v_mul_f32_e32 v1, 0x3fb8aa3b, v42
	v_mul_f32_e32 v48, 0x3fb8aa3b, v48
	v_mul_f32_e32 v22, 0x3fb8aa3b, v22
	v_exp_f32_e32 v5, v5
	v_exp_f32_e32 v41, v41
	v_exp_f32_e32 v1, v1
	v_exp_f32_e32 v48, v48
	v_exp_f32_e32 v22, v22
	v_mul_f32_e32 v2, 0x3fb8aa3b, v2
	v_exp_f32_e32 v2, v2
	v_mul_f32_e32 v5, v5, v52
	v_mul_f32_e32 v41, v0, v41
	v_mul_f32_e32 v52, v0, v1
	v_mul_f32_e32 v48, v0, v48
	v_mul_f32_e32 v22, v0, v22
	v_sub_f32_e32 v0, v44, v42
	v_mul_f32_e32 v0, 0x3fb8aa3b, v0
	v_mul_f32_e32 v54, v2, v39
	v_exp_f32_e32 v0, v0
	v_mul_f32_e32 v1, 0x3fb8aa3b, v23
	v_mul_f32_e32 v2, 0x3fb8aa3b, v43
	v_exp_f32_e32 v1, v1
	v_exp_f32_e32 v2, v2
	v_mul_f32_e32 v39, v0, v39
	v_mul_f32_e32 v0, 0x3e000000, v36
	v_mul_f32_e32 v36, v0, v1
	v_mul_f32_e32 v42, v0, v2
	v_sub_f32_e32 v1, v23, v3
	v_sub_f32_e32 v2, v3, v23
	v_sub_f32_e32 v3, v43, v45
	v_mul_f32_e32 v1, 0x3fb8aa3b, v1
	v_mul_f32_e32 v2, 0x3fb8aa3b, v2
	v_mul_f32_e32 v3, 0x3fb8aa3b, v3
	v_exp_f32_e32 v1, v1
	v_exp_f32_e32 v2, v2
	v_exp_f32_e32 v3, v3
	v_sub_f32_e32 v23, v45, v43
	v_mul_f32_e32 v43, v0, v1
	v_mul_f32_e32 v44, v2, v28
	v_mul_f32_e32 v45, v0, v3
	v_cvt_pk_bf16_f32 v0, v29, v31
	v_cvt_pk_bf16_f32 v1, v34, v37
	v_cvt_pk_bf16_f32 v2, v49, v25
	v_mul_lo_u32 v25, v170, s53
	v_add3_u32 v25, 0, v25, v176
	v_cvt_pk_bf16_f32 v3, v41, v36
	ds_write_b128 v25, v[0:3] offset:54272
	v_cvt_pk_bf16_f32 v0, v13, v17
	v_cvt_pk_bf16_f32 v1, v33, v38
	v_cvt_pk_bf16_f32 v2, v18, v46
	v_mul_lo_u32 v13, v170, s55
	v_cvt_pk_bf16_f32 v3, v52, v42
	ds_write_b128 v25, v[0:3] offset:54400
	v_cvt_pk_bf16_f32 v0, v11, v21
	v_cvt_pk_bf16_f32 v1, v32, v35
	v_cvt_pk_bf16_f32 v2, v40, v47
	v_add3_u32 v11, s54, v13, v176
	v_cvt_pk_bf16_f32 v3, v48, v43
	ds_write_b128 v11, v[0:3]
	v_cvt_pk_bf16_f32 v0, v8, v12
	v_cvt_pk_bf16_f32 v1, v30, v27
	v_cvt_pk_bf16_f32 v2, v50, v51
	v_add3_u32 v8, s56, v13, v176
	v_mul_f32_e32 v23, 0x3fb8aa3b, v23
	v_cvt_pk_bf16_f32 v3, v54, v44
	ds_write_b128 v8, v[0:3]
	v_cvt_pk_bf16_f32 v0, v7, v10
	v_cvt_pk_bf16_f32 v1, v26, v15
	v_cvt_pk_bf16_f32 v2, v24, v53
	v_add3_u32 v7, s57, v13, v176
	v_exp_f32_e32 v23, v23
	v_cvt_pk_bf16_f32 v3, v22, v45
	ds_write_b128 v7, v[0:3]
	v_cvt_pk_bf16_f32 v0, v6, v9
	v_cvt_pk_bf16_f32 v1, v14, v20
	v_cvt_pk_bf16_f32 v2, v4, v5
	v_lshl_add_u64 v[4:5], v[118:119], 0, s[8:9]
	v_mov_b32_e32 v17, v177
	v_lshl_add_u64 v[8:9], v[4:5], 0, v[16:17]
	v_add_co_u32_e32 v4, vcc, s34, v8
	v_mul_f32_e32 v23, v23, v28
	s_nop 0
	v_addc_co_u32_e32 v5, vcc, 0, v9, vcc
	v_cvt_pk_bf16_f32 v3, v39, v23
	global_load_dwordx4 v[4:7], v[4:5], off offset:2048
	v_lshl_add_u64 v[8:9], v[8:9], 0, s[2:3]
	global_load_dwordx4 v[8:11], v[8:9], off offset:16
	v_add3_u32 v12, s58, v13, v176
	ds_write_b128 v12, v[0:3]
	v_lshlrev_b32_e32 v16, 1, v170
	v_mul_u32_u24_e32 v17, 0x900, v19
	v_add3_u32 v16, s59, v16, v17
	s_cselect_b64 s[2:3], -1, 0
	s_addk_i32 s0, 0xf000
	s_lshr_b32 s0, s0, 11
	s_ashr_i32 s1, s12, 5
	s_cmp_gt_i32 s61, 63
	s_cselect_b64 s[18:19], -1, 0
	s_and_b64 vcc, s[18:19], exec
	s_cselect_b32 s13, s0, s1
	s_lshl_b32 s7, s13, 2
	s_or_b32 s16, s7, 2
	s_lshl_b64 s[0:1], s[16:17], 18
	s_add_u32 s0, s25, s0
	s_addc_u32 s1, s26, s1
	s_or_b32 s14, s7, 3
	s_waitcnt vmcnt(1)
	v_lshlrev_b32_e32 v0, 16, v4
	v_cvt_pk_bf16_f32 v0, v0, v177
	v_and_b32_e32 v1, 0xffff0000, v4
	ds_write_b16 v16, v0
	v_cvt_pk_bf16_f32 v0, v1, v177
	v_lshlrev_b32_e32 v2, 16, v5
	ds_write_b16 v16, v0 offset:144
	v_cvt_pk_bf16_f32 v0, v2, v177
	v_and_b32_e32 v3, 0xffff0000, v5
	ds_write_b16 v16, v0 offset:288
	v_cvt_pk_bf16_f32 v0, v3, v177
	v_lshlrev_b32_e32 v4, 16, v6
	ds_write_b16 v16, v0 offset:432
	v_cvt_pk_bf16_f32 v0, v4, v177
	v_and_b32_e32 v5, 0xffff0000, v6
	ds_write_b16 v16, v0 offset:576
	v_cvt_pk_bf16_f32 v0, v5, v177
	v_lshlrev_b32_e32 v6, 16, v7
	ds_write_b16 v16, v0 offset:720
	v_cvt_pk_bf16_f32 v0, v6, v177
	v_and_b32_e32 v7, 0xffff0000, v7
	ds_write_b16 v16, v0 offset:864
	v_cvt_pk_bf16_f32 v0, v7, v177
	s_waitcnt vmcnt(0)
	v_lshlrev_b32_e32 v12, 16, v8
	ds_write_b16 v16, v0 offset:1008
	v_cvt_pk_bf16_f32 v0, v12, v177
	v_and_b32_e32 v8, 0xffff0000, v8
	ds_write_b16 v16, v0 offset:1152
	v_cvt_pk_bf16_f32 v0, v8, v177
	v_lshlrev_b32_e32 v13, 16, v9
	ds_write_b16 v16, v0 offset:1296
	v_cvt_pk_bf16_f32 v0, v13, v177
	v_and_b32_e32 v9, 0xffff0000, v9
	ds_write_b16 v16, v0 offset:1440
	v_cvt_pk_bf16_f32 v0, v9, v177
	v_lshlrev_b32_e32 v14, 16, v10
	ds_write_b16 v16, v0 offset:1584
	v_cvt_pk_bf16_f32 v0, v14, v177
	v_and_b32_e32 v10, 0xffff0000, v10
	ds_write_b16 v16, v0 offset:1728
	v_cvt_pk_bf16_f32 v0, v10, v177
	v_lshlrev_b32_e32 v15, 16, v11
	ds_write_b16 v16, v0 offset:1872
	v_cvt_pk_bf16_f32 v0, v15, v177
	v_and_b32_e32 v11, 0xffff0000, v11
	ds_write_b16 v16, v0 offset:2016
	v_cvt_pk_bf16_f32 v0, v11, v177
	ds_write_b16 v16, v0 offset:2160
	v_lshlrev_b32_e32 v0, 11, v171
	v_and_b32_e32 v2, 0x7800, v0
	v_mov_b32_e32 v3, v177
	v_lshl_add_u64 v[0:1], s[0:1], 0, v[2:3]
	s_lshl_b64 s[0:1], s[14:15], 18
	s_add_u32 s0, s25, s0
	s_addc_u32 s1, s26, s1
	v_lshl_add_u64 v[2:3], s[0:1], 0, v[2:3]
	s_cbranch_vccz .LBB0_1370
	v_readlane_b32 s68, v254, 16
	v_readlane_b32 s69, v254, 17
	s_sub_i32 s70, s61, 64
	s_lshl_b32 s70, s70, 3
	s_or_b32 s70, s70, s24
	s_mov_b32 s71, 0
	s_lshl_b64 s[70:71], s[70:71], 16
	s_add_u32 s68, s68, s70
	s_addc_u32 s69, s69, s71
	s_add_u32 s70, s68, 0x8000
	s_addc_u32 s71, s69, 0
	v_lshlrev_b32_e32 v186, 4, v171
	global_load_dwordx4 v[132:135], v186, s[68:69]
	global_load_dwordx4 v[128:131], v186, s[70:71]
	v_add_u32_e32 v187, 0x2000, v186
	global_load_dwordx4 v[140:143], v187, s[68:69]
	global_load_dwordx4 v[136:139], v187, s[70:71]
	v_add_u32_e32 v187, 0x4000, v186
	global_load_dwordx4 v[148:151], v187, s[68:69]
	global_load_dwordx4 v[144:147], v187, s[70:71]
	v_add_u32_e32 v187, 0x6000, v186
	global_load_dwordx4 v[156:159], v187, s[68:69]
	global_load_dwordx4 v[152:155], v187, s[70:71]
	v_ashrrev_i32_e32 v117, 31, v116
	s_branch .LBB0_1354
	v_ashrrev_i32_e32 v4, 4, v171
	v_ashrrev_i32_e32 v5, 31, v4
	v_lshlrev_b64 v[4:5], 2, v[4:5]
	v_lshl_add_u64 v[6:7], v[0:1], 0, v[4:5]
	v_lshl_add_u64 v[4:5], v[2:3], 0, v[4:5]
	global_load_dword v132, v[6:7], off
	global_load_dword v133, v[6:7], off offset:512
	global_load_dword v134, v[6:7], off offset:1024
	global_load_dword v135, v[6:7], off offset:1536
	global_load_dword v128, v[4:5], off
	global_load_dword v129, v[4:5], off offset:512
	global_load_dword v130, v[4:5], off offset:1024
	global_load_dword v131, v[4:5], off offset:1536
	v_cndmask_b32_e64 v4, 0, 1, s[18:19]
	v_cmp_ne_u32_e64 s[0:1], 1, v4
	s_andn2_b64 vcc, exec, s[18:19]
	s_cbranch_vccz .LBB0_1371
